# stack: LDS-DMA m0-write/address-add reorder (drops s_nop per DMA issue, 47 sites) + EpiQKV rope prefetch on top of v10
# baseline (speedup 1.0000x reference)
; #define PG8_STAGE(bufoff, gbase, voff) do { _Pragma("unroll") for (int _i = 0; _i < 2; ++_i) \
;         __builtin_amdgcn_global_load_lds((const unsigned*)((const char*)(gbase) + (voff)[_i]), (PG8_LAS unsigned*)(lds + (bufoff) + ldsw + _i * 8192), 16, 0, 0); } while (0)
; #define PG8_LDA(dst, b, h) do { _Pragma("unroll") for (int m = 0; m < 4; ++m) _Pragma("unroll") for (int k = 0; k < 2; ++k) dst[m][k] = *(const PG8_LAS bf16x8*)(lds + PG8_SA(b, h) + aoff + m * 2048 + k * 1024); } while (0)
; #define PG8_LDB(dst, b, h) do { _Pragma("unroll") for (int n = 0; n < 2; ++n) _Pragma("unroll") for (int k = 0; k < 2; ++k) dst[n][k] = *(const PG8_LAS bf16x8*)(lds + PG8_SB(b, h) + boff + n * 2048 + k * 1024); } while (0)
; #define PG8_MMA(ai, bj, At, Bt) do { __builtin_amdgcn_s_setprio(1); _Pragma("unroll") for (int m = 0; m < 4; ++m) _Pragma("unroll") for (int n = 0; n < 2; ++n) _Pragma("unroll") for (int k = 0; k < 2; ++k) \
;         acc[ai][bj][m][n] = __builtin_amdgcn_mfma_f32_16x16x32_bf16(Bt[n][k], At[m][k], acc[ai][bj][m][n], 0, 0, 0); __builtin_amdgcn_s_setprio(0); } while (0)
; #define PG8_WAIT_V(n) asm volatile("s_waitcnt vmcnt(" #n ")" ::: "memory")
; #define PG8_WAIT_L(n) asm volatile("s_waitcnt lgkmcnt(" #n ")" ::: "memory")
; #define PG8_BAR __builtin_amdgcn_s_barrier()
; #define PG8_SCHED __builtin_amdgcn_sched_barrier(0)
; template <class Epi, class Sched, bool ALIGN_EPI = false, bool SP2 = false>
; __device__ __forceinline__ void gemm_phase(PG8_LAS unsigned char* lds, const Gemm g, const Sched& S, const Epi& E) {
;     ...
;         for (int t = 0; t < nt; t += 2) {
;             const bool last = (t == nt - 2);
;             const char* a1 = cA + (size_t)(t + 1) * kstep;
;             const char* a2 = last ? nA : cA + (size_t)(t + 2) * kstep; const char* b2 = last ? nB : cB + (size_t)(t + 2) * kstep;
;             const char* a3 = a2 + kstep; const char* b3 = b2 + kstep;
;             if (last && has_next) S.a_ready(nxt);
;             if constexpr (SP2) {
;             PG8_LDB(B0, 0, 0); PG8_LDB(B1, 0, 1); PG8_SCHED; PG8_LDA(At, 0, 0); PG8_STAGE(PG8_SA(1, 1), a1 + hstepA, voffA);
;             PG8_WAIT_V(8); PG8_WAIT_L(0); PG8_BAR; PG8_MMA(0, 0, At, B0); PG8_MMA(0, 1, At, B1); PG8_BAR; PG8_SCHED;
;             PG8_LDA(At, 0, 1); PG8_STAGE(PG8_SB(0, 0), b2, voffB); PG8_STAGE(PG8_SB(0, 1), b2 + hstepB, voffB); PG8_STAGE(PG8_SA(0, 0), a2, voffA);
.LBB0_171:
	s_add_u32 s50, s8, 0xfffc0080
	s_addc_u32 s51, s9, -1
	s_add_i32 s60, 0, 0x10000
	s_cmp_eq_u32 s59, 12
	s_cselect_b32 s53, s11, s51
	s_cselect_b32 s52, s37, s50
	s_cselect_b32 s51, s35, s58
	s_cselect_b32 s50, s54, s55
	s_add_i32 s62, 0, 0x14000
	v_add_u32_e32 v76, s60, v162
	v_add_u32_e32 v158, s62, v162
	ds_read_b128 v[64:67], v76
	ds_read_b128 v[68:71], v76 offset:1024
	ds_read_b128 v[72:75], v76 offset:2048
	ds_read_b128 v[76:79], v76 offset:3072
	ds_read_b128 v[154:157], v158
	ds_read_b128 v[164:167], v158 offset:1024
	ds_read_b128 v[168:171], v158 offset:2048
	ds_read_b128 v[172:175], v158 offset:3072
	v_lshl_add_u64 v[158:159], s[8:9], 0, v[150:151]
	s_add_i32 m0, s57, 0xc000
	ds_read_b128 v[176:179], v163
	ds_read_b128 v[180:183], v163 offset:1024
	ds_read_b128 v[184:187], v163 offset:2048
	ds_read_b128 v[194:197], v163 offset:3072
	ds_read_b128 v[230:233], v163 offset:4096
	ds_read_b128 v[234:237], v163 offset:5120
	ds_read_b128 v[238:241], v163 offset:6144
	ds_read_b128 v[242:245], v163 offset:7168
	global_load_lds_dwordx4 v[158:159], off
	s_add_i32 m0, s57, 0xe000
	v_lshl_add_u64 v[158:159], s[8:9], 0, v[152:153]
	global_load_lds_dwordx4 v[158:159], off
	s_waitcnt vmcnt(8)
	s_waitcnt lgkmcnt(0)
	s_barrier
	s_setprio 1
	s_waitcnt lgkmcnt(0)
	v_mfma_f32_16x16x32_bf16 v[140:143], v[64:67], v[176:179], v[140:143]
	v_mfma_f32_16x16x32_bf16 v[136:139], v[72:75], v[176:179], v[136:139]
	v_mfma_f32_16x16x32_bf16 v[124:127], v[64:67], v[184:187], v[124:127]
	v_mfma_f32_16x16x32_bf16 v[120:123], v[72:75], v[184:187], v[120:123]
	v_mfma_f32_16x16x32_bf16 v[108:111], v[64:67], v[230:233], v[108:111]
	v_mfma_f32_16x16x32_bf16 v[104:107], v[72:75], v[230:233], v[104:107]
	v_mfma_f32_16x16x32_bf16 v[92:95], v[64:67], v[238:241], v[92:95]
	v_mfma_f32_16x16x32_bf16 v[88:91], v[72:75], v[238:241], v[88:91]
	v_mfma_f32_16x16x32_bf16 v[140:143], v[68:71], v[180:183], v[140:143]
	v_mfma_f32_16x16x32_bf16 v[136:139], v[76:79], v[180:183], v[136:139]
	v_mfma_f32_16x16x32_bf16 v[124:127], v[68:71], v[194:197], v[124:127]
	v_mfma_f32_16x16x32_bf16 v[120:123], v[76:79], v[194:197], v[120:123]
	v_mfma_f32_16x16x32_bf16 v[108:111], v[68:71], v[234:237], v[108:111]
	v_mfma_f32_16x16x32_bf16 v[104:107], v[76:79], v[234:237], v[104:107]
	v_mfma_f32_16x16x32_bf16 v[92:95], v[68:71], v[242:245], v[92:95]
	v_mfma_f32_16x16x32_bf16 v[88:91], v[76:79], v[242:245], v[88:91]
	s_setprio 0
	s_setprio 1
	v_mfma_f32_16x16x32_bf16 v[132:135], v[154:157], v[176:179], v[132:135]
	v_mfma_f32_16x16x32_bf16 v[128:131], v[168:171], v[176:179], v[128:131]
	v_mfma_f32_16x16x32_bf16 v[116:119], v[154:157], v[184:187], v[116:119]
	v_mfma_f32_16x16x32_bf16 v[112:115], v[168:171], v[184:187], v[112:115]
	v_mfma_f32_16x16x32_bf16 v[100:103], v[154:157], v[230:233], v[100:103]
	v_mfma_f32_16x16x32_bf16 v[96:99], v[168:171], v[230:233], v[96:99]
	v_mfma_f32_16x16x32_bf16 v[84:87], v[154:157], v[238:241], v[84:87]
	v_mfma_f32_16x16x32_bf16 v[80:83], v[168:171], v[238:241], v[80:83]
	v_mfma_f32_16x16x32_bf16 v[132:135], v[164:167], v[180:183], v[132:135]
	v_mfma_f32_16x16x32_bf16 v[128:131], v[172:175], v[180:183], v[128:131]
	v_mfma_f32_16x16x32_bf16 v[116:119], v[164:167], v[194:197], v[116:119]
	v_mfma_f32_16x16x32_bf16 v[112:115], v[172:175], v[194:197], v[112:115]
	v_mfma_f32_16x16x32_bf16 v[100:103], v[164:167], v[234:237], v[100:103]
	v_mfma_f32_16x16x32_bf16 v[96:99], v[172:175], v[234:237], v[96:99]
	v_mfma_f32_16x16x32_bf16 v[84:87], v[164:167], v[242:245], v[84:87]
	v_mfma_f32_16x16x32_bf16 v[80:83], v[172:175], v[242:245], v[80:83]
	s_setprio 0
	s_barrier
	s_add_i32 s60, s60, s69
	v_lshl_add_u64 v[158:159], s[50:51], 0, v[188:189]
	s_mov_b32 m0, s60
	ds_read_b128 v[176:179], v163 offset:16384
	ds_read_b128 v[180:183], v163 offset:17408
	ds_read_b128 v[184:187], v163 offset:18432
	ds_read_b128 v[194:197], v163 offset:19456
	ds_read_b128 v[230:233], v163 offset:20480
	ds_read_b128 v[234:237], v163 offset:21504
	ds_read_b128 v[238:241], v163 offset:22528
	ds_read_b128 v[242:245], v163 offset:23552
	global_load_lds_dwordx4 v[158:159], off
	s_add_i32 m0, s60, 0x2000
	s_add_u32 s60, s50, 0x40000
	v_lshl_add_u64 v[246:247], s[50:51], 0, v[148:149]
	s_addc_u32 s61, s51, 0
	s_add_i32 s62, s62, s69
	global_load_lds_dwordx4 v[246:247], off
	v_lshl_add_u64 v[248:249], s[60:61], 0, v[188:189]
	s_mov_b32 m0, s62
	v_lshl_add_u64 v[250:251], s[52:53], 0, v[146:147]
	global_load_lds_dwordx4 v[248:249], off
	s_add_i32 m0, s62, 0x2000
	v_lshl_add_u64 v[248:249], s[60:61], 0, v[148:149]
	global_load_lds_dwordx4 v[248:249], off
	s_mov_b32 m0, s57
	v_lshl_add_u64 v[248:249], s[52:53], 0, v[144:145]
	global_load_lds_dwordx4 v[248:249], off
	s_mov_b32 m0, s78
	s_nop 0
	global_load_lds_dwordx4 v[250:251], off
	s_waitcnt vmcnt(8)
	s_waitcnt lgkmcnt(0)
	s_barrier
; #define PG8_STAGE(bufoff, gbase, voff) do { _Pragma("unroll") for (int _i = 0; _i < 2; ++_i) \
;         __builtin_amdgcn_global_load_lds((const unsigned*)((const char*)(gbase) + (voff)[_i]), (PG8_LAS unsigned*)(lds + (bufoff) + ldsw + _i * 8192), 16, 0, 0); } while (0)
; #define PG8_LDA(dst, b, h) do { _Pragma("unroll") for (int m = 0; m < 4; ++m) _Pragma("unroll") for (int k = 0; k < 2; ++k) dst[m][k] = *(const PG8_LAS bf16x8*)(lds + PG8_SA(b, h) + aoff + m * 2048 + k * 1024); } while (0)
; #define PG8_LDB(dst, b, h) do { _Pragma("unroll") for (int n = 0; n < 2; ++n) _Pragma("unroll") for (int k = 0; k < 2; ++k) dst[n][k] = *(const PG8_LAS bf16x8*)(lds + PG8_SB(b, h) + boff + n * 2048 + k * 1024); } while (0)
; #define PG8_MMA(ai, bj, At, Bt) do { __builtin_amdgcn_s_setprio(1); _Pragma("unroll") for (int m = 0; m < 4; ++m) _Pragma("unroll") for (int n = 0; n < 2; ++n) _Pragma("unroll") for (int k = 0; k < 2; ++k) \
;         acc[ai][bj][m][n] = __builtin_amdgcn_mfma_f32_16x16x32_bf16(Bt[n][k], At[m][k], acc[ai][bj][m][n], 0, 0, 0); __builtin_amdgcn_s_setprio(0); } while (0)
; #define PG8_WAIT_V(n) asm volatile("s_waitcnt vmcnt(" #n ")" ::: "memory")
; #define PG8_WAIT_L(n) asm volatile("s_waitcnt lgkmcnt(" #n ")" ::: "memory")
; #define PG8_BAR __builtin_amdgcn_s_barrier()
; #define PG8_SCHED __builtin_amdgcn_sched_barrier(0)
; template <class Epi, class Sched, bool ALIGN_EPI = false, bool SP2 = false>
; __device__ __forceinline__ void gemm_phase(PG8_LAS unsigned char* lds, const Gemm g, const Sched& S, const Epi& E) {
;     ...
;             PG8_WAIT_V(8); PG8_WAIT_L(0); PG8_BAR; PG8_MMA(1, 0, At, B0); PG8_MMA(1, 1, At, B1); PG8_BAR; PG8_SCHED;
;             PG8_LDB(B0, 1, 0); PG8_LDB(B1, 1, 1); PG8_SCHED; PG8_LDA(At, 1, 0); PG8_STAGE(PG8_SA(0, 1), a2 + hstepA, voffA);
;             PG8_WAIT_V(8); PG8_WAIT_L(0); PG8_BAR; PG8_MMA(0, 0, At, B0); PG8_MMA(0, 1, At, B1); PG8_BAR; PG8_SCHED;
	s_setprio 1
	s_waitcnt lgkmcnt(0)
	v_mfma_f32_16x16x32_bf16 v[60:63], v[64:67], v[176:179], v[60:63]
	v_mfma_f32_16x16x32_bf16 v[56:59], v[72:75], v[176:179], v[56:59]
	v_mfma_f32_16x16x32_bf16 v[44:47], v[64:67], v[184:187], v[44:47]
	v_mfma_f32_16x16x32_bf16 v[40:43], v[72:75], v[184:187], v[40:43]
	v_mfma_f32_16x16x32_bf16 v[28:31], v[64:67], v[230:233], v[28:31]
	v_mfma_f32_16x16x32_bf16 v[24:27], v[72:75], v[230:233], v[24:27]
	v_mfma_f32_16x16x32_bf16 v[12:15], v[64:67], v[238:241], v[12:15]
	v_mfma_f32_16x16x32_bf16 v[8:11], v[72:75], v[238:241], v[8:11]
	v_mfma_f32_16x16x32_bf16 v[60:63], v[68:71], v[180:183], v[60:63]
	v_mfma_f32_16x16x32_bf16 v[56:59], v[76:79], v[180:183], v[56:59]
	v_mfma_f32_16x16x32_bf16 v[44:47], v[68:71], v[194:197], v[44:47]
	v_mfma_f32_16x16x32_bf16 v[40:43], v[76:79], v[194:197], v[40:43]
	v_mfma_f32_16x16x32_bf16 v[28:31], v[68:71], v[234:237], v[28:31]
	v_mfma_f32_16x16x32_bf16 v[24:27], v[76:79], v[234:237], v[24:27]
	v_mfma_f32_16x16x32_bf16 v[12:15], v[68:71], v[242:245], v[12:15]
	v_mfma_f32_16x16x32_bf16 v[8:11], v[76:79], v[242:245], v[8:11]
	s_setprio 0
	s_setprio 1
	v_mfma_f32_16x16x32_bf16 v[52:55], v[154:157], v[176:179], v[52:55]
	v_mfma_f32_16x16x32_bf16 v[48:51], v[168:171], v[176:179], v[48:51]
	v_mfma_f32_16x16x32_bf16 v[36:39], v[154:157], v[184:187], v[36:39]
	v_mfma_f32_16x16x32_bf16 v[32:35], v[168:171], v[184:187], v[32:35]
	v_mfma_f32_16x16x32_bf16 v[20:23], v[154:157], v[230:233], v[20:23]
	v_mfma_f32_16x16x32_bf16 v[16:19], v[168:171], v[230:233], v[16:19]
	v_mfma_f32_16x16x32_bf16 v[4:7], v[154:157], v[238:241], v[4:7]
	v_mfma_f32_16x16x32_bf16 v[0:3], v[168:171], v[238:241], v[0:3]
	v_mfma_f32_16x16x32_bf16 v[52:55], v[164:167], v[180:183], v[52:55]
	v_mfma_f32_16x16x32_bf16 v[48:51], v[172:175], v[180:183], v[48:51]
	v_mfma_f32_16x16x32_bf16 v[36:39], v[164:167], v[194:197], v[36:39]
	v_mfma_f32_16x16x32_bf16 v[32:35], v[172:175], v[194:197], v[32:35]
	v_mfma_f32_16x16x32_bf16 v[20:23], v[164:167], v[234:237], v[20:23]
	v_mfma_f32_16x16x32_bf16 v[16:19], v[172:175], v[234:237], v[16:19]
	v_mfma_f32_16x16x32_bf16 v[4:7], v[164:167], v[242:245], v[4:7]
	v_mfma_f32_16x16x32_bf16 v[0:3], v[172:175], v[242:245], v[0:3]
	s_setprio 0
	s_barrier
	s_add_i32 s60, 0, 0x18000
	s_add_i32 s61, 0, 0x1c000
	v_add_u32_e32 v76, s60, v162
	v_add_u32_e32 v172, s61, v162
	ds_read_b128 v[64:67], v76
	ds_read_b128 v[68:71], v76 offset:1024
	ds_read_b128 v[72:75], v76 offset:2048
	ds_read_b128 v[76:79], v76 offset:3072
	ds_read_b128 v[154:157], v172
	ds_read_b128 v[164:167], v172 offset:1024
	ds_read_b128 v[168:171], v172 offset:2048
	ds_read_b128 v[172:175], v172 offset:3072
	s_add_u32 s52, s52, 0x40000
	s_addc_u32 s53, s53, 0
	s_mov_b32 m0, s81
	v_lshl_add_u64 v[252:253], s[52:53], 0, v[144:145]
	ds_read_b128 v[176:179], v163 offset:32768
	ds_read_b128 v[180:183], v163 offset:33792
	ds_read_b128 v[184:187], v163 offset:34816
	ds_read_b128 v[194:197], v163 offset:35840
	ds_read_b128 v[230:233], v163 offset:36864
	ds_read_b128 v[234:237], v163 offset:37888
	ds_read_b128 v[238:241], v163 offset:38912
	ds_read_b128 v[242:245], v163 offset:39936
	global_load_lds_dwordx4 v[252:253], off
	s_mov_b32 m0, s80
	v_lshl_add_u64 v[252:253], s[52:53], 0, v[146:147]
	global_load_lds_dwordx4 v[252:253], off
	s_waitcnt vmcnt(8)
	s_waitcnt lgkmcnt(0)
	s_barrier
	s_setprio 1
	s_waitcnt lgkmcnt(0)
	v_mfma_f32_16x16x32_bf16 v[140:143], v[64:67], v[176:179], v[140:143]
	v_mfma_f32_16x16x32_bf16 v[136:139], v[72:75], v[176:179], v[136:139]
	v_mfma_f32_16x16x32_bf16 v[124:127], v[64:67], v[184:187], v[124:127]
	v_mfma_f32_16x16x32_bf16 v[120:123], v[72:75], v[184:187], v[120:123]
	v_mfma_f32_16x16x32_bf16 v[108:111], v[64:67], v[230:233], v[108:111]
	v_mfma_f32_16x16x32_bf16 v[104:107], v[72:75], v[230:233], v[104:107]
	v_mfma_f32_16x16x32_bf16 v[92:95], v[64:67], v[238:241], v[92:95]
	v_mfma_f32_16x16x32_bf16 v[88:91], v[72:75], v[238:241], v[88:91]
	v_mfma_f32_16x16x32_bf16 v[140:143], v[68:71], v[180:183], v[140:143]
	v_mfma_f32_16x16x32_bf16 v[136:139], v[76:79], v[180:183], v[136:139]
	v_mfma_f32_16x16x32_bf16 v[124:127], v[68:71], v[194:197], v[124:127]
	v_mfma_f32_16x16x32_bf16 v[120:123], v[76:79], v[194:197], v[120:123]
	v_mfma_f32_16x16x32_bf16 v[108:111], v[68:71], v[234:237], v[108:111]
	v_mfma_f32_16x16x32_bf16 v[104:107], v[76:79], v[234:237], v[104:107]
	v_mfma_f32_16x16x32_bf16 v[92:95], v[68:71], v[242:245], v[92:95]
	v_mfma_f32_16x16x32_bf16 v[88:91], v[76:79], v[242:245], v[88:91]
	s_setprio 0
	s_setprio 1
	v_mfma_f32_16x16x32_bf16 v[132:135], v[154:157], v[176:179], v[132:135]
	v_mfma_f32_16x16x32_bf16 v[128:131], v[168:171], v[176:179], v[128:131]
	v_mfma_f32_16x16x32_bf16 v[116:119], v[154:157], v[184:187], v[116:119]
	v_mfma_f32_16x16x32_bf16 v[112:115], v[168:171], v[184:187], v[112:115]
	v_mfma_f32_16x16x32_bf16 v[100:103], v[154:157], v[230:233], v[100:103]
	v_mfma_f32_16x16x32_bf16 v[96:99], v[168:171], v[230:233], v[96:99]
	v_mfma_f32_16x16x32_bf16 v[84:87], v[154:157], v[238:241], v[84:87]
	v_mfma_f32_16x16x32_bf16 v[80:83], v[168:171], v[238:241], v[80:83]
	v_mfma_f32_16x16x32_bf16 v[132:135], v[164:167], v[180:183], v[132:135]
	v_mfma_f32_16x16x32_bf16 v[128:131], v[172:175], v[180:183], v[128:131]
	v_mfma_f32_16x16x32_bf16 v[116:119], v[164:167], v[194:197], v[116:119]
	v_mfma_f32_16x16x32_bf16 v[112:115], v[172:175], v[194:197], v[112:115]
	v_mfma_f32_16x16x32_bf16 v[100:103], v[164:167], v[234:237], v[100:103]
	v_mfma_f32_16x16x32_bf16 v[96:99], v[172:175], v[234:237], v[96:99]
	v_mfma_f32_16x16x32_bf16 v[84:87], v[164:167], v[242:245], v[84:87]
	v_mfma_f32_16x16x32_bf16 v[80:83], v[172:175], v[242:245], v[80:83]
	s_setprio 0
	s_barrier
; #define PG8_STAGE(bufoff, gbase, voff) do { _Pragma("unroll") for (int _i = 0; _i < 2; ++_i) \
;         __builtin_amdgcn_global_load_lds((const unsigned*)((const char*)(gbase) + (voff)[_i]), (PG8_LAS unsigned*)(lds + (bufoff) + ldsw + _i * 8192), 16, 0, 0); } while (0)
; #define PG8_LDA(dst, b, h) do { _Pragma("unroll") for (int m = 0; m < 4; ++m) _Pragma("unroll") for (int k = 0; k < 2; ++k) dst[m][k] = *(const PG8_LAS bf16x8*)(lds + PG8_SA(b, h) + aoff + m * 2048 + k * 1024); } while (0)
; #define PG8_MMA(ai, bj, At, Bt) do { __builtin_amdgcn_s_setprio(1); _Pragma("unroll") for (int m = 0; m < 4; ++m) _Pragma("unroll") for (int n = 0; n < 2; ++n) _Pragma("unroll") for (int k = 0; k < 2; ++k) \
;         acc[ai][bj][m][n] = __builtin_amdgcn_mfma_f32_16x16x32_bf16(Bt[n][k], At[m][k], acc[ai][bj][m][n], 0, 0, 0); __builtin_amdgcn_s_setprio(0); } while (0)
; #define PG8_WAIT_V(n) asm volatile("s_waitcnt vmcnt(" #n ")" ::: "memory")
; #define PG8_WAIT_L(n) asm volatile("s_waitcnt lgkmcnt(" #n ")" ::: "memory")
; #define PG8_BAR __builtin_amdgcn_s_barrier()
; #define PG8_SCHED __builtin_amdgcn_sched_barrier(0)
; template <class Epi, class Sched, bool ALIGN_EPI = false, bool SP2 = false>
; __device__ __forceinline__ void gemm_phase(PG8_LAS unsigned char* lds, const Gemm g, const Sched& S, const Epi& E) {
;     ...
;             PG8_LDA(At, 1, 1); PG8_STAGE(PG8_SB(1, 0), b3, voffB); PG8_STAGE(PG8_SB(1, 1), b3 + hstepB, voffB); PG8_STAGE(PG8_SA(1, 0), a3, voffA);
;             PG8_WAIT_V(8); PG8_WAIT_L(0); PG8_BAR; PG8_MMA(1, 0, At, B0); PG8_MMA(1, 1, At, B1); PG8_BAR; PG8_SCHED;
;     ...
;         if constexpr (ALIGN_EPI) { if (wr == 0) PG8_BAR; }
	s_add_i32 s52, s60, s69
	v_lshl_add_u64 v[158:159], v[158:159], 0, s[94:95]
	s_mov_b32 m0, s52
	ds_read_b128 v[176:179], v163 offset:49152
	ds_read_b128 v[180:183], v163 offset:50176
	ds_read_b128 v[184:187], v163 offset:51200
	ds_read_b128 v[194:197], v163 offset:52224
	ds_read_b128 v[230:233], v163 offset:53248
	ds_read_b128 v[234:237], v163 offset:54272
	ds_read_b128 v[238:241], v163 offset:55296
	ds_read_b128 v[242:245], v163 offset:56320
	global_load_lds_dwordx4 v[158:159], off
	s_add_i32 m0, s52, 0x2000
	s_add_u32 s50, s50, 0x40080
	v_lshl_add_u64 v[158:159], v[246:247], 0, s[94:95]
	s_addc_u32 s51, s51, 0
	s_add_i32 s52, s61, s69
	global_load_lds_dwordx4 v[158:159], off
	s_mov_b32 m0, s52
	v_lshl_add_u64 v[158:159], s[50:51], 0, v[188:189]
	global_load_lds_dwordx4 v[158:159], off
	s_add_i32 m0, s52, 0x2000
	v_lshl_add_u64 v[158:159], s[50:51], 0, v[148:149]
	global_load_lds_dwordx4 v[158:159], off
	s_mov_b32 m0, s2
	v_lshl_add_u64 v[158:159], v[248:249], 0, s[94:95]
	global_load_lds_dwordx4 v[158:159], off
	s_mov_b32 m0, s4
	v_lshl_add_u64 v[158:159], v[250:251], 0, s[94:95]
	global_load_lds_dwordx4 v[158:159], off
	s_waitcnt vmcnt(8)
	s_waitcnt lgkmcnt(0)
	s_barrier
	s_setprio 1
	s_waitcnt lgkmcnt(0)
	v_mfma_f32_16x16x32_bf16 v[60:63], v[64:67], v[176:179], v[60:63]
	v_mfma_f32_16x16x32_bf16 v[56:59], v[72:75], v[176:179], v[56:59]
	v_mfma_f32_16x16x32_bf16 v[44:47], v[64:67], v[184:187], v[44:47]
	v_mfma_f32_16x16x32_bf16 v[40:43], v[72:75], v[184:187], v[40:43]
	v_mfma_f32_16x16x32_bf16 v[28:31], v[64:67], v[230:233], v[28:31]
	v_mfma_f32_16x16x32_bf16 v[24:27], v[72:75], v[230:233], v[24:27]
	v_mfma_f32_16x16x32_bf16 v[12:15], v[64:67], v[238:241], v[12:15]
	v_mfma_f32_16x16x32_bf16 v[8:11], v[72:75], v[238:241], v[8:11]
	v_mfma_f32_16x16x32_bf16 v[60:63], v[68:71], v[180:183], v[60:63]
	v_mfma_f32_16x16x32_bf16 v[56:59], v[76:79], v[180:183], v[56:59]
	v_mfma_f32_16x16x32_bf16 v[44:47], v[68:71], v[194:197], v[44:47]
	v_mfma_f32_16x16x32_bf16 v[40:43], v[76:79], v[194:197], v[40:43]
	v_mfma_f32_16x16x32_bf16 v[28:31], v[68:71], v[234:237], v[28:31]
	v_mfma_f32_16x16x32_bf16 v[24:27], v[76:79], v[234:237], v[24:27]
	v_mfma_f32_16x16x32_bf16 v[12:15], v[68:71], v[242:245], v[12:15]
	v_mfma_f32_16x16x32_bf16 v[8:11], v[76:79], v[242:245], v[8:11]
	s_setprio 0
	s_setprio 1
	v_mfma_f32_16x16x32_bf16 v[52:55], v[154:157], v[176:179], v[52:55]
	v_mfma_f32_16x16x32_bf16 v[48:51], v[168:171], v[176:179], v[48:51]
	v_mfma_f32_16x16x32_bf16 v[36:39], v[154:157], v[184:187], v[36:39]
	v_mfma_f32_16x16x32_bf16 v[32:35], v[168:171], v[184:187], v[32:35]
	v_mfma_f32_16x16x32_bf16 v[20:23], v[154:157], v[230:233], v[20:23]
	v_mfma_f32_16x16x32_bf16 v[16:19], v[168:171], v[230:233], v[16:19]
	v_mfma_f32_16x16x32_bf16 v[4:7], v[154:157], v[238:241], v[4:7]
	v_mfma_f32_16x16x32_bf16 v[0:3], v[168:171], v[238:241], v[0:3]
	v_mfma_f32_16x16x32_bf16 v[52:55], v[164:167], v[180:183], v[52:55]
	v_mfma_f32_16x16x32_bf16 v[48:51], v[172:175], v[180:183], v[48:51]
	v_mfma_f32_16x16x32_bf16 v[36:39], v[164:167], v[194:197], v[36:39]
	v_mfma_f32_16x16x32_bf16 v[32:35], v[172:175], v[194:197], v[32:35]
	v_mfma_f32_16x16x32_bf16 v[20:23], v[164:167], v[234:237], v[20:23]
	v_mfma_f32_16x16x32_bf16 v[16:19], v[172:175], v[234:237], v[16:19]
	v_mfma_f32_16x16x32_bf16 v[4:7], v[164:167], v[242:245], v[4:7]
	v_mfma_f32_16x16x32_bf16 v[0:3], v[172:175], v[242:245], v[0:3]
	s_setprio 0
	s_barrier
	s_add_i32 s59, s59, 2
	s_add_u32 s8, s8, 0x100
	s_addc_u32 s9, s9, 0
	s_add_u32 s55, s55, 0x100
	s_addc_u32 s58, s58, 0
	s_cmp_gt_u32 s59, 13
	s_cbranch_scc0 .LBB0_171
	s_and_b64 vcc, exec, s[30:31]
	s_cbranch_vccz .LBB0_174
	s_barrier

; #define PG8_STAGE(bufoff, gbase, voff) do { _Pragma("unroll") for (int _i = 0; _i < 2; ++_i) \
;         __builtin_amdgcn_global_load_lds((const unsigned*)((const char*)(gbase) + (voff)[_i]), (PG8_LAS unsigned*)(lds + (bufoff) + ldsw + _i * 8192), 16, 0, 0); } while (0)
; #define PG8_LDA(dst, b, h) do { _Pragma("unroll") for (int m = 0; m < 4; ++m) _Pragma("unroll") for (int k = 0; k < 2; ++k) dst[m][k] = *(const PG8_LAS bf16x8*)(lds + PG8_SA(b, h) + aoff + m * 2048 + k * 1024); } while (0)
; #define PG8_LDB(dst, b, h) do { _Pragma("unroll") for (int n = 0; n < 2; ++n) _Pragma("unroll") for (int k = 0; k < 2; ++k) dst[n][k] = *(const PG8_LAS bf16x8*)(lds + PG8_SB(b, h) + boff + n * 2048 + k * 1024); } while (0)
; #define PG8_MMA(ai, bj, At, Bt) do { __builtin_amdgcn_s_setprio(1); _Pragma("unroll") for (int m = 0; m < 4; ++m) _Pragma("unroll") for (int n = 0; n < 2; ++n) _Pragma("unroll") for (int k = 0; k < 2; ++k) \
;         acc[ai][bj][m][n] = __builtin_amdgcn_mfma_f32_16x16x32_bf16(Bt[n][k], At[m][k], acc[ai][bj][m][n], 0, 0, 0); __builtin_amdgcn_s_setprio(0); } while (0)
; #define PG8_WAIT_V(n) asm volatile("s_waitcnt vmcnt(" #n ")" ::: "memory")
; #define PG8_WAIT_L(n) asm volatile("s_waitcnt lgkmcnt(" #n ")" ::: "memory")
; #define PG8_BAR __builtin_amdgcn_s_barrier()
; #define PG8_SCHED __builtin_amdgcn_sched_barrier(0)
; template <class Epi, class Sched, bool ALIGN_EPI = false, bool SP2 = false>
; __device__ __forceinline__ void gemm_phase(PG8_LAS unsigned char* lds, const Gemm g, const Sched& S, const Epi& E) {
;     ...
;         for (int t = 0; t < nt; t += 2) {
;             const bool last = (t == nt - 2);
;             const char* a1 = cA + (size_t)(t + 1) * kstep;
;             const char* a2 = last ? nA : cA + (size_t)(t + 2) * kstep; const char* b2 = last ? nB : cB + (size_t)(t + 2) * kstep;
;             const char* a3 = a2 + kstep; const char* b3 = b2 + kstep;
;             if (last && has_next) S.a_ready(nxt);
;             if constexpr (SP2) {
;             PG8_LDB(B0, 0, 0); PG8_LDB(B1, 0, 1); PG8_SCHED; PG8_LDA(At, 0, 0); PG8_STAGE(PG8_SA(1, 1), a1 + hstepA, voffA);
;             PG8_WAIT_V(8); PG8_WAIT_L(0); PG8_BAR; PG8_MMA(0, 0, At, B0); PG8_MMA(0, 1, At, B1); PG8_BAR; PG8_SCHED;
;             PG8_LDA(At, 0, 1); PG8_STAGE(PG8_SB(0, 0), b2, voffB); PG8_STAGE(PG8_SB(0, 1), b2 + hstepB, voffB); PG8_STAGE(PG8_SA(0, 0), a2, voffA);
.LBB0_712:
	s_add_u32 s28, s26, 0xfffc0080
	s_addc_u32 s29, s27, -1
	s_add_i32 s33, 0, 0x10000
	s_cmp_eq_u32 s19, 12
	s_cselect_b32 s31, s1, s29
	s_cselect_b32 s30, s2, s28
	s_cselect_b32 s29, s3, s17
	s_cselect_b32 s28, s4, s9
	s_add_i32 s51, 0, 0x14000
	v_add_u32_e32 v154, s33, v144
	v_add_u32_e32 v170, s51, v144
	ds_read_b128 v[138:141], v154
	ds_read_b128 v[146:149], v154 offset:1024
	ds_read_b128 v[150:153], v154 offset:2048
	ds_read_b128 v[154:157], v154 offset:3072
	ds_read_b128 v[158:161], v170
	ds_read_b128 v[162:165], v170 offset:1024
	ds_read_b128 v[166:169], v170 offset:2048
	ds_read_b128 v[170:173], v170 offset:3072
	v_lshl_add_u64 v[186:187], s[26:27], 0, v[134:135]
	s_add_i32 m0, s25, 0xc000
	ds_read_b128 v[174:177], v145
	ds_read_b128 v[178:181], v145 offset:1024
	ds_read_b128 v[182:185], v145 offset:2048
	ds_read_b128 v[192:195], v145 offset:3072
	ds_read_b128 v[230:233], v145 offset:4096
	ds_read_b128 v[234:237], v145 offset:5120
	ds_read_b128 v[238:241], v145 offset:6144
	ds_read_b128 v[242:245], v145 offset:7168
	global_load_lds_dwordx4 v[186:187], off
	s_add_i32 m0, s25, 0xe000
	v_lshl_add_u64 v[186:187], s[26:27], 0, v[136:137]
	global_load_lds_dwordx4 v[186:187], off
	s_waitcnt vmcnt(8)
	s_waitcnt lgkmcnt(0)
	s_barrier
	s_setprio 1
	s_waitcnt lgkmcnt(0)
	v_mfma_f32_16x16x32_bf16 v[124:127], v[138:141], v[174:177], v[124:127]
	v_mfma_f32_16x16x32_bf16 v[120:123], v[150:153], v[174:177], v[120:123]
	v_mfma_f32_16x16x32_bf16 v[108:111], v[138:141], v[182:185], v[108:111]
	v_mfma_f32_16x16x32_bf16 v[104:107], v[150:153], v[182:185], v[104:107]
	v_mfma_f32_16x16x32_bf16 v[92:95], v[138:141], v[230:233], v[92:95]
	v_mfma_f32_16x16x32_bf16 v[88:91], v[150:153], v[230:233], v[88:91]
	v_mfma_f32_16x16x32_bf16 v[76:79], v[138:141], v[238:241], v[76:79]
	v_mfma_f32_16x16x32_bf16 v[72:75], v[150:153], v[238:241], v[72:75]
	v_mfma_f32_16x16x32_bf16 v[124:127], v[146:149], v[178:181], v[124:127]
	v_mfma_f32_16x16x32_bf16 v[120:123], v[154:157], v[178:181], v[120:123]
	v_mfma_f32_16x16x32_bf16 v[108:111], v[146:149], v[192:195], v[108:111]
	v_mfma_f32_16x16x32_bf16 v[104:107], v[154:157], v[192:195], v[104:107]
	v_mfma_f32_16x16x32_bf16 v[92:95], v[146:149], v[234:237], v[92:95]
	v_mfma_f32_16x16x32_bf16 v[88:91], v[154:157], v[234:237], v[88:91]
	v_mfma_f32_16x16x32_bf16 v[76:79], v[146:149], v[242:245], v[76:79]
	v_mfma_f32_16x16x32_bf16 v[72:75], v[154:157], v[242:245], v[72:75]
	s_setprio 0
	s_setprio 1
	v_mfma_f32_16x16x32_bf16 v[116:119], v[158:161], v[174:177], v[116:119]
	v_mfma_f32_16x16x32_bf16 v[112:115], v[166:169], v[174:177], v[112:115]
	v_mfma_f32_16x16x32_bf16 v[100:103], v[158:161], v[182:185], v[100:103]
	v_mfma_f32_16x16x32_bf16 v[96:99], v[166:169], v[182:185], v[96:99]
	v_mfma_f32_16x16x32_bf16 v[84:87], v[158:161], v[230:233], v[84:87]
	v_mfma_f32_16x16x32_bf16 v[80:83], v[166:169], v[230:233], v[80:83]
	v_mfma_f32_16x16x32_bf16 v[68:71], v[158:161], v[238:241], v[68:71]
	v_mfma_f32_16x16x32_bf16 v[64:67], v[166:169], v[238:241], v[64:67]
	v_mfma_f32_16x16x32_bf16 v[116:119], v[162:165], v[178:181], v[116:119]
	v_mfma_f32_16x16x32_bf16 v[112:115], v[170:173], v[178:181], v[112:115]
	v_mfma_f32_16x16x32_bf16 v[100:103], v[162:165], v[192:195], v[100:103]
	v_mfma_f32_16x16x32_bf16 v[96:99], v[170:173], v[192:195], v[96:99]
	v_mfma_f32_16x16x32_bf16 v[84:87], v[162:165], v[234:237], v[84:87]
	v_mfma_f32_16x16x32_bf16 v[80:83], v[170:173], v[234:237], v[80:83]
	v_mfma_f32_16x16x32_bf16 v[68:71], v[162:165], v[242:245], v[68:71]
	v_mfma_f32_16x16x32_bf16 v[64:67], v[170:173], v[242:245], v[64:67]
	s_setprio 0
	s_barrier
	s_add_i32 s33, s33, s39
	v_lshl_add_u64 v[186:187], s[28:29], 0, v[188:189]
	s_mov_b32 m0, s33
	ds_read_b128 v[174:177], v145 offset:16384
	ds_read_b128 v[178:181], v145 offset:17408
	ds_read_b128 v[182:185], v145 offset:18432
	ds_read_b128 v[192:195], v145 offset:19456
	ds_read_b128 v[230:233], v145 offset:20480
	ds_read_b128 v[234:237], v145 offset:21504
	ds_read_b128 v[238:241], v145 offset:22528
	ds_read_b128 v[242:245], v145 offset:23552
	global_load_lds_dwordx4 v[186:187], off
	s_add_i32 m0, s33, 0x2000
	s_add_u32 s52, s28, 0x40000
	v_lshl_add_u64 v[196:197], s[28:29], 0, v[132:133]
	s_addc_u32 s53, s29, 0
	s_add_i32 s33, s51, s39
	global_load_lds_dwordx4 v[196:197], off
	v_lshl_add_u64 v[246:247], s[52:53], 0, v[188:189]
	s_mov_b32 m0, s33
	v_lshl_add_u64 v[248:249], s[30:31], 0, v[130:131]
	global_load_lds_dwordx4 v[246:247], off
	s_add_i32 m0, s33, 0x2000
	v_lshl_add_u64 v[246:247], s[52:53], 0, v[132:133]
	global_load_lds_dwordx4 v[246:247], off
	s_mov_b32 m0, s25
	v_lshl_add_u64 v[246:247], s[30:31], 0, v[128:129]
	global_load_lds_dwordx4 v[246:247], off
	s_mov_b32 m0, s40
	s_nop 0
	global_load_lds_dwordx4 v[248:249], off
	s_waitcnt vmcnt(8)
	s_waitcnt lgkmcnt(0)
	s_barrier
; #define PG8_STAGE(bufoff, gbase, voff) do { _Pragma("unroll") for (int _i = 0; _i < 2; ++_i) \
;         __builtin_amdgcn_global_load_lds((const unsigned*)((const char*)(gbase) + (voff)[_i]), (PG8_LAS unsigned*)(lds + (bufoff) + ldsw + _i * 8192), 16, 0, 0); } while (0)
; #define PG8_LDA(dst, b, h) do { _Pragma("unroll") for (int m = 0; m < 4; ++m) _Pragma("unroll") for (int k = 0; k < 2; ++k) dst[m][k] = *(const PG8_LAS bf16x8*)(lds + PG8_SA(b, h) + aoff + m * 2048 + k * 1024); } while (0)
; #define PG8_LDB(dst, b, h) do { _Pragma("unroll") for (int n = 0; n < 2; ++n) _Pragma("unroll") for (int k = 0; k < 2; ++k) dst[n][k] = *(const PG8_LAS bf16x8*)(lds + PG8_SB(b, h) + boff + n * 2048 + k * 1024); } while (0)
; #define PG8_MMA(ai, bj, At, Bt) do { __builtin_amdgcn_s_setprio(1); _Pragma("unroll") for (int m = 0; m < 4; ++m) _Pragma("unroll") for (int n = 0; n < 2; ++n) _Pragma("unroll") for (int k = 0; k < 2; ++k) \
;         acc[ai][bj][m][n] = __builtin_amdgcn_mfma_f32_16x16x32_bf16(Bt[n][k], At[m][k], acc[ai][bj][m][n], 0, 0, 0); __builtin_amdgcn_s_setprio(0); } while (0)
; #define PG8_WAIT_V(n) asm volatile("s_waitcnt vmcnt(" #n ")" ::: "memory")
; #define PG8_WAIT_L(n) asm volatile("s_waitcnt lgkmcnt(" #n ")" ::: "memory")
; #define PG8_BAR __builtin_amdgcn_s_barrier()
; #define PG8_SCHED __builtin_amdgcn_sched_barrier(0)
; template <class Epi, class Sched, bool ALIGN_EPI = false, bool SP2 = false>
; __device__ __forceinline__ void gemm_phase(PG8_LAS unsigned char* lds, const Gemm g, const Sched& S, const Epi& E) {
;     ...
;             PG8_WAIT_V(8); PG8_WAIT_L(0); PG8_BAR; PG8_MMA(1, 0, At, B0); PG8_MMA(1, 1, At, B1); PG8_BAR; PG8_SCHED;
;             PG8_LDB(B0, 1, 0); PG8_LDB(B1, 1, 1); PG8_SCHED; PG8_LDA(At, 1, 0); PG8_STAGE(PG8_SA(0, 1), a2 + hstepA, voffA);
;             PG8_WAIT_V(8); PG8_WAIT_L(0); PG8_BAR; PG8_MMA(0, 0, At, B0); PG8_MMA(0, 1, At, B1); PG8_BAR; PG8_SCHED;
	s_setprio 1
	s_waitcnt lgkmcnt(0)
	v_mfma_f32_16x16x32_bf16 v[60:63], v[138:141], v[174:177], v[60:63]
	v_mfma_f32_16x16x32_bf16 v[56:59], v[150:153], v[174:177], v[56:59]
	v_mfma_f32_16x16x32_bf16 v[44:47], v[138:141], v[182:185], v[44:47]
	v_mfma_f32_16x16x32_bf16 v[40:43], v[150:153], v[182:185], v[40:43]
	v_mfma_f32_16x16x32_bf16 v[28:31], v[138:141], v[230:233], v[28:31]
	v_mfma_f32_16x16x32_bf16 v[24:27], v[150:153], v[230:233], v[24:27]
	v_mfma_f32_16x16x32_bf16 v[12:15], v[138:141], v[238:241], v[12:15]
	v_mfma_f32_16x16x32_bf16 v[8:11], v[150:153], v[238:241], v[8:11]
	v_mfma_f32_16x16x32_bf16 v[60:63], v[146:149], v[178:181], v[60:63]
	v_mfma_f32_16x16x32_bf16 v[56:59], v[154:157], v[178:181], v[56:59]
	v_mfma_f32_16x16x32_bf16 v[44:47], v[146:149], v[192:195], v[44:47]
	v_mfma_f32_16x16x32_bf16 v[40:43], v[154:157], v[192:195], v[40:43]
	v_mfma_f32_16x16x32_bf16 v[28:31], v[146:149], v[234:237], v[28:31]
	v_mfma_f32_16x16x32_bf16 v[24:27], v[154:157], v[234:237], v[24:27]
	v_mfma_f32_16x16x32_bf16 v[12:15], v[146:149], v[242:245], v[12:15]
	v_mfma_f32_16x16x32_bf16 v[8:11], v[154:157], v[242:245], v[8:11]
	s_setprio 0
	s_setprio 1
	v_mfma_f32_16x16x32_bf16 v[52:55], v[158:161], v[174:177], v[52:55]
	v_mfma_f32_16x16x32_bf16 v[48:51], v[166:169], v[174:177], v[48:51]
	v_mfma_f32_16x16x32_bf16 v[36:39], v[158:161], v[182:185], v[36:39]
	v_mfma_f32_16x16x32_bf16 v[32:35], v[166:169], v[182:185], v[32:35]
	v_mfma_f32_16x16x32_bf16 v[20:23], v[158:161], v[230:233], v[20:23]
	v_mfma_f32_16x16x32_bf16 v[16:19], v[166:169], v[230:233], v[16:19]
	v_mfma_f32_16x16x32_bf16 v[4:7], v[158:161], v[238:241], v[4:7]
	v_mfma_f32_16x16x32_bf16 v[0:3], v[166:169], v[238:241], v[0:3]
	v_mfma_f32_16x16x32_bf16 v[52:55], v[162:165], v[178:181], v[52:55]
	v_mfma_f32_16x16x32_bf16 v[48:51], v[170:173], v[178:181], v[48:51]
	v_mfma_f32_16x16x32_bf16 v[36:39], v[162:165], v[192:195], v[36:39]
	v_mfma_f32_16x16x32_bf16 v[32:35], v[170:173], v[192:195], v[32:35]
	v_mfma_f32_16x16x32_bf16 v[20:23], v[162:165], v[234:237], v[20:23]
	v_mfma_f32_16x16x32_bf16 v[16:19], v[170:173], v[234:237], v[16:19]
	v_mfma_f32_16x16x32_bf16 v[4:7], v[162:165], v[242:245], v[4:7]
	v_mfma_f32_16x16x32_bf16 v[0:3], v[170:173], v[242:245], v[0:3]
	s_setprio 0
	s_barrier
	s_add_i32 s33, 0, 0x18000
	s_add_i32 s51, 0, 0x1c000
	v_add_u32_e32 v154, s33, v144
	v_add_u32_e32 v170, s51, v144
	ds_read_b128 v[138:141], v154
	ds_read_b128 v[146:149], v154 offset:1024
	ds_read_b128 v[150:153], v154 offset:2048
	ds_read_b128 v[154:157], v154 offset:3072
	ds_read_b128 v[158:161], v170
	ds_read_b128 v[162:165], v170 offset:1024
	ds_read_b128 v[166:169], v170 offset:2048
	ds_read_b128 v[170:173], v170 offset:3072
	s_add_u32 s30, s30, 0x40000
	s_addc_u32 s31, s31, 0
	s_mov_b32 m0, s41
	v_lshl_add_u64 v[250:251], s[30:31], 0, v[128:129]
	ds_read_b128 v[174:177], v145 offset:32768
	ds_read_b128 v[178:181], v145 offset:33792
	ds_read_b128 v[182:185], v145 offset:34816
	ds_read_b128 v[192:195], v145 offset:35840
	ds_read_b128 v[230:233], v145 offset:36864
	ds_read_b128 v[234:237], v145 offset:37888
	ds_read_b128 v[238:241], v145 offset:38912
	ds_read_b128 v[242:245], v145 offset:39936
	global_load_lds_dwordx4 v[250:251], off
	s_mov_b32 m0, s42
	v_lshl_add_u64 v[250:251], s[30:31], 0, v[130:131]
	global_load_lds_dwordx4 v[250:251], off
	s_waitcnt vmcnt(8)
	s_waitcnt lgkmcnt(0)
	s_barrier
	s_setprio 1
	s_waitcnt lgkmcnt(0)
	v_mfma_f32_16x16x32_bf16 v[124:127], v[138:141], v[174:177], v[124:127]
	v_mfma_f32_16x16x32_bf16 v[120:123], v[150:153], v[174:177], v[120:123]
	v_mfma_f32_16x16x32_bf16 v[108:111], v[138:141], v[182:185], v[108:111]
	v_mfma_f32_16x16x32_bf16 v[104:107], v[150:153], v[182:185], v[104:107]
	v_mfma_f32_16x16x32_bf16 v[92:95], v[138:141], v[230:233], v[92:95]
	v_mfma_f32_16x16x32_bf16 v[88:91], v[150:153], v[230:233], v[88:91]
	v_mfma_f32_16x16x32_bf16 v[76:79], v[138:141], v[238:241], v[76:79]
	v_mfma_f32_16x16x32_bf16 v[72:75], v[150:153], v[238:241], v[72:75]
	v_mfma_f32_16x16x32_bf16 v[124:127], v[146:149], v[178:181], v[124:127]
	v_mfma_f32_16x16x32_bf16 v[120:123], v[154:157], v[178:181], v[120:123]
	v_mfma_f32_16x16x32_bf16 v[108:111], v[146:149], v[192:195], v[108:111]
	v_mfma_f32_16x16x32_bf16 v[104:107], v[154:157], v[192:195], v[104:107]
	v_mfma_f32_16x16x32_bf16 v[92:95], v[146:149], v[234:237], v[92:95]
	v_mfma_f32_16x16x32_bf16 v[88:91], v[154:157], v[234:237], v[88:91]
	v_mfma_f32_16x16x32_bf16 v[76:79], v[146:149], v[242:245], v[76:79]
	v_mfma_f32_16x16x32_bf16 v[72:75], v[154:157], v[242:245], v[72:75]
	s_setprio 0
	s_setprio 1
	v_mfma_f32_16x16x32_bf16 v[116:119], v[158:161], v[174:177], v[116:119]
	v_mfma_f32_16x16x32_bf16 v[112:115], v[166:169], v[174:177], v[112:115]
	v_mfma_f32_16x16x32_bf16 v[100:103], v[158:161], v[182:185], v[100:103]
	v_mfma_f32_16x16x32_bf16 v[96:99], v[166:169], v[182:185], v[96:99]
	v_mfma_f32_16x16x32_bf16 v[84:87], v[158:161], v[230:233], v[84:87]
	v_mfma_f32_16x16x32_bf16 v[80:83], v[166:169], v[230:233], v[80:83]
	v_mfma_f32_16x16x32_bf16 v[68:71], v[158:161], v[238:241], v[68:71]
	v_mfma_f32_16x16x32_bf16 v[64:67], v[166:169], v[238:241], v[64:67]
	v_mfma_f32_16x16x32_bf16 v[116:119], v[162:165], v[178:181], v[116:119]
	v_mfma_f32_16x16x32_bf16 v[112:115], v[170:173], v[178:181], v[112:115]
	v_mfma_f32_16x16x32_bf16 v[100:103], v[162:165], v[192:195], v[100:103]
	v_mfma_f32_16x16x32_bf16 v[96:99], v[170:173], v[192:195], v[96:99]
	v_mfma_f32_16x16x32_bf16 v[84:87], v[162:165], v[234:237], v[84:87]
	v_mfma_f32_16x16x32_bf16 v[80:83], v[170:173], v[234:237], v[80:83]
	v_mfma_f32_16x16x32_bf16 v[68:71], v[162:165], v[242:245], v[68:71]
	v_mfma_f32_16x16x32_bf16 v[64:67], v[170:173], v[242:245], v[64:67]
	s_setprio 0
	s_barrier
; #define PG8_STAGE(bufoff, gbase, voff) do { _Pragma("unroll") for (int _i = 0; _i < 2; ++_i) \
;         __builtin_amdgcn_global_load_lds((const unsigned*)((const char*)(gbase) + (voff)[_i]), (PG8_LAS unsigned*)(lds + (bufoff) + ldsw + _i * 8192), 16, 0, 0); } while (0)
; #define PG8_LDA(dst, b, h) do { _Pragma("unroll") for (int m = 0; m < 4; ++m) _Pragma("unroll") for (int k = 0; k < 2; ++k) dst[m][k] = *(const PG8_LAS bf16x8*)(lds + PG8_SA(b, h) + aoff + m * 2048 + k * 1024); } while (0)
; #define PG8_MMA(ai, bj, At, Bt) do { __builtin_amdgcn_s_setprio(1); _Pragma("unroll") for (int m = 0; m < 4; ++m) _Pragma("unroll") for (int n = 0; n < 2; ++n) _Pragma("unroll") for (int k = 0; k < 2; ++k) \
;         acc[ai][bj][m][n] = __builtin_amdgcn_mfma_f32_16x16x32_bf16(Bt[n][k], At[m][k], acc[ai][bj][m][n], 0, 0, 0); __builtin_amdgcn_s_setprio(0); } while (0)
; #define PG8_WAIT_V(n) asm volatile("s_waitcnt vmcnt(" #n ")" ::: "memory")
; #define PG8_WAIT_L(n) asm volatile("s_waitcnt lgkmcnt(" #n ")" ::: "memory")
; #define PG8_BAR __builtin_amdgcn_s_barrier()
; #define PG8_SCHED __builtin_amdgcn_sched_barrier(0)
; template <class Epi, class Sched, bool ALIGN_EPI = false, bool SP2 = false>
; __device__ __forceinline__ void gemm_phase(PG8_LAS unsigned char* lds, const Gemm g, const Sched& S, const Epi& E) {
;     ...
;             PG8_LDA(At, 1, 1); PG8_STAGE(PG8_SB(1, 0), b3, voffB); PG8_STAGE(PG8_SB(1, 1), b3 + hstepB, voffB); PG8_STAGE(PG8_SA(1, 0), a3, voffA);
;             PG8_WAIT_V(8); PG8_WAIT_L(0); PG8_BAR; PG8_MMA(1, 0, At, B0); PG8_MMA(1, 1, At, B1); PG8_BAR; PG8_SCHED;
;     ...
;         if constexpr (ALIGN_EPI) { if (wr == 0) PG8_BAR; }
	s_add_i32 s30, s33, s39
	v_lshl_add_u64 v[186:187], v[186:187], 0, s[94:95]
	s_mov_b32 m0, s30
	ds_read_b128 v[174:177], v145 offset:49152
	ds_read_b128 v[178:181], v145 offset:50176
	ds_read_b128 v[182:185], v145 offset:51200
	ds_read_b128 v[192:195], v145 offset:52224
	ds_read_b128 v[230:233], v145 offset:53248
	ds_read_b128 v[234:237], v145 offset:54272
	ds_read_b128 v[238:241], v145 offset:55296
	ds_read_b128 v[242:245], v145 offset:56320
	global_load_lds_dwordx4 v[186:187], off
	s_add_i32 m0, s30, 0x2000
	s_add_u32 s28, s28, 0x40080
	v_lshl_add_u64 v[186:187], v[196:197], 0, s[94:95]
	s_addc_u32 s29, s29, 0
	s_add_i32 s30, s51, s39
	global_load_lds_dwordx4 v[186:187], off
	s_mov_b32 m0, s30
	v_lshl_add_u64 v[186:187], s[28:29], 0, v[188:189]
	global_load_lds_dwordx4 v[186:187], off
	s_add_i32 m0, s30, 0x2000
	v_lshl_add_u64 v[186:187], s[28:29], 0, v[132:133]
	global_load_lds_dwordx4 v[186:187], off
	s_mov_b32 m0, s47
	v_lshl_add_u64 v[186:187], v[246:247], 0, s[94:95]
	global_load_lds_dwordx4 v[186:187], off
	s_mov_b32 m0, s48
	v_lshl_add_u64 v[186:187], v[248:249], 0, s[94:95]
	global_load_lds_dwordx4 v[186:187], off
	s_waitcnt vmcnt(8)
	s_waitcnt lgkmcnt(0)
	s_barrier
	s_setprio 1
	s_waitcnt lgkmcnt(0)
	v_mfma_f32_16x16x32_bf16 v[60:63], v[138:141], v[174:177], v[60:63]
	v_mfma_f32_16x16x32_bf16 v[56:59], v[150:153], v[174:177], v[56:59]
	v_mfma_f32_16x16x32_bf16 v[44:47], v[138:141], v[182:185], v[44:47]
	v_mfma_f32_16x16x32_bf16 v[40:43], v[150:153], v[182:185], v[40:43]
	v_mfma_f32_16x16x32_bf16 v[28:31], v[138:141], v[230:233], v[28:31]
	v_mfma_f32_16x16x32_bf16 v[24:27], v[150:153], v[230:233], v[24:27]
	v_mfma_f32_16x16x32_bf16 v[12:15], v[138:141], v[238:241], v[12:15]
	v_mfma_f32_16x16x32_bf16 v[8:11], v[150:153], v[238:241], v[8:11]
	v_mfma_f32_16x16x32_bf16 v[60:63], v[146:149], v[178:181], v[60:63]
	v_mfma_f32_16x16x32_bf16 v[56:59], v[154:157], v[178:181], v[56:59]
	v_mfma_f32_16x16x32_bf16 v[44:47], v[146:149], v[192:195], v[44:47]
	v_mfma_f32_16x16x32_bf16 v[40:43], v[154:157], v[192:195], v[40:43]
	v_mfma_f32_16x16x32_bf16 v[28:31], v[146:149], v[234:237], v[28:31]
	v_mfma_f32_16x16x32_bf16 v[24:27], v[154:157], v[234:237], v[24:27]
	v_mfma_f32_16x16x32_bf16 v[12:15], v[146:149], v[242:245], v[12:15]
	v_mfma_f32_16x16x32_bf16 v[8:11], v[154:157], v[242:245], v[8:11]
	s_setprio 0
	s_setprio 1
	v_mfma_f32_16x16x32_bf16 v[52:55], v[158:161], v[174:177], v[52:55]
	v_mfma_f32_16x16x32_bf16 v[48:51], v[166:169], v[174:177], v[48:51]
	v_mfma_f32_16x16x32_bf16 v[36:39], v[158:161], v[182:185], v[36:39]
	v_mfma_f32_16x16x32_bf16 v[32:35], v[166:169], v[182:185], v[32:35]
	v_mfma_f32_16x16x32_bf16 v[20:23], v[158:161], v[230:233], v[20:23]
	v_mfma_f32_16x16x32_bf16 v[16:19], v[166:169], v[230:233], v[16:19]
	v_mfma_f32_16x16x32_bf16 v[4:7], v[158:161], v[238:241], v[4:7]
	v_mfma_f32_16x16x32_bf16 v[0:3], v[166:169], v[238:241], v[0:3]
	v_mfma_f32_16x16x32_bf16 v[52:55], v[162:165], v[178:181], v[52:55]
	v_mfma_f32_16x16x32_bf16 v[48:51], v[170:173], v[178:181], v[48:51]
	v_mfma_f32_16x16x32_bf16 v[36:39], v[162:165], v[192:195], v[36:39]
	v_mfma_f32_16x16x32_bf16 v[32:35], v[170:173], v[192:195], v[32:35]
	v_mfma_f32_16x16x32_bf16 v[20:23], v[162:165], v[234:237], v[20:23]
	v_mfma_f32_16x16x32_bf16 v[16:19], v[170:173], v[234:237], v[16:19]
	v_mfma_f32_16x16x32_bf16 v[4:7], v[162:165], v[242:245], v[4:7]
	v_mfma_f32_16x16x32_bf16 v[0:3], v[170:173], v[242:245], v[0:3]
	s_setprio 0
	s_barrier
	s_add_i32 s19, s19, 2
	s_add_u32 s26, s26, 0x100
	s_addc_u32 s27, s27, 0
	s_add_u32 s9, s9, 0x100
	s_addc_u32 s17, s17, 0
	s_cmp_gt_u32 s19, 13
	s_cbranch_scc0 .LBB0_712
	s_and_b64 vcc, exec, s[14:15]
	s_cbranch_vccz .LBB0_715
	s_barrier

; #define PG8_STAGE(bufoff, gbase, voff) do { _Pragma("unroll") for (int _i = 0; _i < 2; ++_i) \
;         __builtin_amdgcn_global_load_lds((const unsigned*)((const char*)(gbase) + (voff)[_i]), (PG8_LAS unsigned*)(lds + (bufoff) + ldsw + _i * 8192), 16, 0, 0); } while (0)
; #define PG8_LDA(dst, b, h) do { _Pragma("unroll") for (int m = 0; m < 4; ++m) _Pragma("unroll") for (int k = 0; k < 2; ++k) dst[m][k] = *(const PG8_LAS bf16x8*)(lds + PG8_SA(b, h) + aoff + m * 2048 + k * 1024); } while (0)
; #define PG8_LDB(dst, b, h) do { _Pragma("unroll") for (int n = 0; n < 2; ++n) _Pragma("unroll") for (int k = 0; k < 2; ++k) dst[n][k] = *(const PG8_LAS bf16x8*)(lds + PG8_SB(b, h) + boff + n * 2048 + k * 1024); } while (0)
; #define PG8_MMA(ai, bj, At, Bt) do { __builtin_amdgcn_s_setprio(1); _Pragma("unroll") for (int m = 0; m < 4; ++m) _Pragma("unroll") for (int n = 0; n < 2; ++n) _Pragma("unroll") for (int k = 0; k < 2; ++k) \
;         acc[ai][bj][m][n] = __builtin_amdgcn_mfma_f32_16x16x32_bf16(Bt[n][k], At[m][k], acc[ai][bj][m][n], 0, 0, 0); __builtin_amdgcn_s_setprio(0); } while (0)
; #define PG8_WAIT_V(n) asm volatile("s_waitcnt vmcnt(" #n ")" ::: "memory")
; #define PG8_WAIT_L(n) asm volatile("s_waitcnt lgkmcnt(" #n ")" ::: "memory")
; #define PG8_BAR __builtin_amdgcn_s_barrier()
; #define PG8_SCHED __builtin_amdgcn_sched_barrier(0)
; template <class Epi, class Sched, bool ALIGN_EPI = false, bool SP2 = false>
; __device__ __forceinline__ void gemm_phase(PG8_LAS unsigned char* lds, const Gemm g, const Sched& S, const Epi& E) {
;     ...
;         for (int t = 0; t < nt; t += 2) {
;             const bool last = (t == nt - 2);
;             const char* a1 = cA + (size_t)(t + 1) * kstep;
;             const char* a2 = last ? nA : cA + (size_t)(t + 2) * kstep; const char* b2 = last ? nB : cB + (size_t)(t + 2) * kstep;
;             const char* a3 = a2 + kstep; const char* b3 = b2 + kstep;
;             if (last && has_next) S.a_ready(nxt);
;             if constexpr (SP2) {
;             PG8_LDB(B0, 0, 0); PG8_LDB(B1, 0, 1); PG8_SCHED; PG8_LDA(At, 0, 0); PG8_STAGE(PG8_SA(1, 1), a1 + hstepA, voffA);
;             PG8_WAIT_V(8); PG8_WAIT_L(0); PG8_BAR; PG8_MMA(0, 0, At, B0); PG8_MMA(0, 1, At, B1); PG8_BAR; PG8_SCHED;
;             PG8_LDA(At, 0, 1); PG8_STAGE(PG8_SB(0, 0), b2, voffB); PG8_STAGE(PG8_SB(0, 1), b2 + hstepB, voffB); PG8_STAGE(PG8_SA(0, 0), a2, voffA);
.LBB0_901:
	s_add_u32 s44, s34, s38
	s_addc_u32 s45, s35, s39
	s_add_u32 s42, s44, 0x100
	s_addc_u32 s43, s45, 0
	s_and_b64 s[40:41], s[36:37], exec
	s_cselect_b32 s41, s27, s43
	s_cselect_b32 s40, s26, s42
	s_add_u32 s38, s30, s38
	s_addc_u32 s39, s31, s39
	s_add_u32 s38, s38, 0x100
	s_addc_u32 s39, s39, 0
	s_add_i32 s72, 0, 0x10000
	s_and_b64 s[36:37], s[36:37], exec
	s_cselect_b32 s43, s25, s39
	s_cselect_b32 s42, s63, s38
	s_add_i32 s37, 0, 0x14000
	s_add_u32 s46, s44, 0x50080
	s_addc_u32 s47, s45, 0
	s_add_i32 s71, s72, s49
	s_add_i32 m0, s51, 0xc000
	s_add_i32 s74, s51, 0xe000
	s_add_i32 s68, s71, 0x2000
	s_add_u32 s44, s42, 0x10000
	v_add_u32_e32 v150, s72, v136
	v_add_u32_e32 v166, s37, v136
	s_addc_u32 s45, s43, 0
	s_add_i32 s70, s37, s49
	ds_read_b128 v[138:141], v150
	ds_read_b128 v[142:145], v150 offset:1024
	ds_read_b128 v[146:149], v150 offset:2048
	ds_read_b128 v[150:153], v150 offset:3072
	ds_read_b128 v[154:157], v166
	ds_read_b128 v[158:161], v166 offset:1024
	ds_read_b128 v[162:165], v166 offset:2048
	ds_read_b128 v[166:169], v166 offset:3072
	s_add_i32 s69, s70, 0x2000
	s_add_i32 s67, 0, 0x18000
	s_add_i32 s66, 0, 0x1c000
	s_add_u32 s38, s40, 0x50000
	s_addc_u32 s39, s41, 0
	s_add_i32 s65, s67, s49
	s_add_i32 s64, s65, 0x2000
	s_add_u32 s36, s42, 0x10080
	s_addc_u32 s37, s43, 0
	s_add_i32 s73, s66, s49
	s_add_i32 s72, s73, 0x2000
	v_lshl_add_u64 v[186:187], s[46:47], 0, v[132:133]
	ds_read_b128 v[170:173], v137
	ds_read_b128 v[174:177], v137 offset:1024
	ds_read_b128 v[178:181], v137 offset:2048
	ds_read_b128 v[182:185], v137 offset:3072
	ds_read_b128 v[192:195], v137 offset:4096
	ds_read_b128 v[230:233], v137 offset:5120
	ds_read_b128 v[234:237], v137 offset:6144
	ds_read_b128 v[238:241], v137 offset:7168
	global_load_lds_dwordx4 v[186:187], off
	s_mov_b32 m0, s74
	v_lshl_add_u64 v[186:187], s[46:47], 0, v[130:131]
	global_load_lds_dwordx4 v[186:187], off
	s_waitcnt vmcnt(8)
	s_waitcnt lgkmcnt(0)
	s_barrier
	s_setprio 1
	s_waitcnt lgkmcnt(0)
	v_mfma_f32_16x16x32_bf16 v[124:127], v[138:141], v[170:173], v[124:127]
	v_mfma_f32_16x16x32_bf16 v[120:123], v[146:149], v[170:173], v[120:123]
	v_mfma_f32_16x16x32_bf16 v[116:119], v[138:141], v[178:181], v[116:119]
	v_mfma_f32_16x16x32_bf16 v[112:115], v[146:149], v[178:181], v[112:115]
	v_mfma_f32_16x16x32_bf16 v[100:103], v[138:141], v[192:195], v[100:103]
	v_mfma_f32_16x16x32_bf16 v[96:99], v[146:149], v[192:195], v[96:99]
	v_mfma_f32_16x16x32_bf16 v[84:87], v[138:141], v[234:237], v[84:87]
	v_mfma_f32_16x16x32_bf16 v[80:83], v[146:149], v[234:237], v[80:83]
	v_mfma_f32_16x16x32_bf16 v[124:127], v[142:145], v[174:177], v[124:127]
	v_mfma_f32_16x16x32_bf16 v[120:123], v[150:153], v[174:177], v[120:123]
	v_mfma_f32_16x16x32_bf16 v[116:119], v[142:145], v[182:185], v[116:119]
	v_mfma_f32_16x16x32_bf16 v[112:115], v[150:153], v[182:185], v[112:115]
	v_mfma_f32_16x16x32_bf16 v[100:103], v[142:145], v[230:233], v[100:103]
	v_mfma_f32_16x16x32_bf16 v[96:99], v[150:153], v[230:233], v[96:99]
	v_mfma_f32_16x16x32_bf16 v[84:87], v[142:145], v[238:241], v[84:87]
	v_mfma_f32_16x16x32_bf16 v[80:83], v[150:153], v[238:241], v[80:83]
	s_setprio 0
	s_setprio 1
	v_mfma_f32_16x16x32_bf16 v[108:111], v[154:157], v[170:173], v[108:111]
	v_mfma_f32_16x16x32_bf16 v[104:107], v[162:165], v[170:173], v[104:107]
	v_mfma_f32_16x16x32_bf16 v[92:95], v[154:157], v[178:181], v[92:95]
	v_mfma_f32_16x16x32_bf16 v[88:91], v[162:165], v[178:181], v[88:91]
	v_mfma_f32_16x16x32_bf16 v[76:79], v[154:157], v[192:195], v[76:79]
	v_mfma_f32_16x16x32_bf16 v[72:75], v[162:165], v[192:195], v[72:75]
	v_mfma_f32_16x16x32_bf16 v[68:71], v[154:157], v[234:237], v[68:71]
	v_mfma_f32_16x16x32_bf16 v[64:67], v[162:165], v[234:237], v[64:67]
	v_mfma_f32_16x16x32_bf16 v[108:111], v[158:161], v[174:177], v[108:111]
	v_mfma_f32_16x16x32_bf16 v[104:107], v[166:169], v[174:177], v[104:107]
	v_mfma_f32_16x16x32_bf16 v[92:95], v[158:161], v[182:185], v[92:95]
	v_mfma_f32_16x16x32_bf16 v[88:91], v[166:169], v[182:185], v[88:91]
	v_mfma_f32_16x16x32_bf16 v[76:79], v[158:161], v[230:233], v[76:79]
	v_mfma_f32_16x16x32_bf16 v[72:75], v[166:169], v[230:233], v[72:75]
	v_mfma_f32_16x16x32_bf16 v[68:71], v[158:161], v[238:241], v[68:71]
	v_mfma_f32_16x16x32_bf16 v[64:67], v[166:169], v[238:241], v[64:67]
	s_setprio 0
	s_barrier
	s_mov_b32 m0, s71
	v_lshl_add_u64 v[186:187], s[42:43], 0, v[188:189]
	ds_read_b128 v[170:173], v137 offset:16384
	ds_read_b128 v[174:177], v137 offset:17408
	ds_read_b128 v[178:181], v137 offset:18432
	ds_read_b128 v[182:185], v137 offset:19456
	ds_read_b128 v[192:195], v137 offset:20480
	ds_read_b128 v[230:233], v137 offset:21504
	ds_read_b128 v[234:237], v137 offset:22528
	ds_read_b128 v[238:241], v137 offset:23552
	global_load_lds_dwordx4 v[186:187], off
	v_lshl_add_u64 v[196:197], s[42:43], 0, v[128:129]
	s_mov_b32 m0, s68
	v_lshl_add_u64 v[242:243], s[44:45], 0, v[188:189]
	global_load_lds_dwordx4 v[196:197], off
	s_mov_b32 m0, s70
	v_lshl_add_u64 v[244:245], s[40:41], 0, v[130:131]
	global_load_lds_dwordx4 v[242:243], off
	s_mov_b32 m0, s69
	v_lshl_add_u64 v[242:243], s[44:45], 0, v[128:129]
	global_load_lds_dwordx4 v[242:243], off
	s_mov_b32 m0, s51
	v_lshl_add_u64 v[242:243], s[40:41], 0, v[132:133]
	global_load_lds_dwordx4 v[242:243], off
	s_mov_b32 m0, s52
	s_nop 0
	global_load_lds_dwordx4 v[244:245], off
	s_waitcnt vmcnt(8)
	s_waitcnt lgkmcnt(0)
	s_barrier
; #define PG8_STAGE(bufoff, gbase, voff) do { _Pragma("unroll") for (int _i = 0; _i < 2; ++_i) \
;         __builtin_amdgcn_global_load_lds((const unsigned*)((const char*)(gbase) + (voff)[_i]), (PG8_LAS unsigned*)(lds + (bufoff) + ldsw + _i * 8192), 16, 0, 0); } while (0)
; #define PG8_LDA(dst, b, h) do { _Pragma("unroll") for (int m = 0; m < 4; ++m) _Pragma("unroll") for (int k = 0; k < 2; ++k) dst[m][k] = *(const PG8_LAS bf16x8*)(lds + PG8_SA(b, h) + aoff + m * 2048 + k * 1024); } while (0)
; #define PG8_LDB(dst, b, h) do { _Pragma("unroll") for (int n = 0; n < 2; ++n) _Pragma("unroll") for (int k = 0; k < 2; ++k) dst[n][k] = *(const PG8_LAS bf16x8*)(lds + PG8_SB(b, h) + boff + n * 2048 + k * 1024); } while (0)
; #define PG8_MMA(ai, bj, At, Bt) do { __builtin_amdgcn_s_setprio(1); _Pragma("unroll") for (int m = 0; m < 4; ++m) _Pragma("unroll") for (int n = 0; n < 2; ++n) _Pragma("unroll") for (int k = 0; k < 2; ++k) \
;         acc[ai][bj][m][n] = __builtin_amdgcn_mfma_f32_16x16x32_bf16(Bt[n][k], At[m][k], acc[ai][bj][m][n], 0, 0, 0); __builtin_amdgcn_s_setprio(0); } while (0)
; #define PG8_WAIT_V(n) asm volatile("s_waitcnt vmcnt(" #n ")" ::: "memory")
; #define PG8_WAIT_L(n) asm volatile("s_waitcnt lgkmcnt(" #n ")" ::: "memory")
; #define PG8_BAR __builtin_amdgcn_s_barrier()
; #define PG8_SCHED __builtin_amdgcn_sched_barrier(0)
; template <class Epi, class Sched, bool ALIGN_EPI = false, bool SP2 = false>
; __device__ __forceinline__ void gemm_phase(PG8_LAS unsigned char* lds, const Gemm g, const Sched& S, const Epi& E) {
;     ...
;             PG8_WAIT_V(8); PG8_WAIT_L(0); PG8_BAR; PG8_MMA(1, 0, At, B0); PG8_MMA(1, 1, At, B1); PG8_BAR; PG8_SCHED;
;             PG8_LDB(B0, 1, 0); PG8_LDB(B1, 1, 1); PG8_SCHED; PG8_LDA(At, 1, 0); PG8_STAGE(PG8_SA(0, 1), a2 + hstepA, voffA);
;             PG8_WAIT_V(8); PG8_WAIT_L(0); PG8_BAR; PG8_MMA(0, 0, At, B0); PG8_MMA(0, 1, At, B1); PG8_BAR; PG8_SCHED;
	s_setprio 1
	s_waitcnt lgkmcnt(0)
	v_mfma_f32_16x16x32_bf16 v[60:63], v[138:141], v[170:173], v[60:63]
	v_mfma_f32_16x16x32_bf16 v[56:59], v[146:149], v[170:173], v[56:59]
	v_mfma_f32_16x16x32_bf16 v[52:55], v[138:141], v[178:181], v[52:55]
	v_mfma_f32_16x16x32_bf16 v[48:51], v[146:149], v[178:181], v[48:51]
	v_mfma_f32_16x16x32_bf16 v[36:39], v[138:141], v[192:195], v[36:39]
	v_mfma_f32_16x16x32_bf16 v[32:35], v[146:149], v[192:195], v[32:35]
	v_mfma_f32_16x16x32_bf16 v[20:23], v[138:141], v[234:237], v[20:23]
	v_mfma_f32_16x16x32_bf16 v[16:19], v[146:149], v[234:237], v[16:19]
	v_mfma_f32_16x16x32_bf16 v[60:63], v[142:145], v[174:177], v[60:63]
	v_mfma_f32_16x16x32_bf16 v[56:59], v[150:153], v[174:177], v[56:59]
	v_mfma_f32_16x16x32_bf16 v[52:55], v[142:145], v[182:185], v[52:55]
	v_mfma_f32_16x16x32_bf16 v[48:51], v[150:153], v[182:185], v[48:51]
	v_mfma_f32_16x16x32_bf16 v[36:39], v[142:145], v[230:233], v[36:39]
	v_mfma_f32_16x16x32_bf16 v[32:35], v[150:153], v[230:233], v[32:35]
	v_mfma_f32_16x16x32_bf16 v[20:23], v[142:145], v[238:241], v[20:23]
	v_mfma_f32_16x16x32_bf16 v[16:19], v[150:153], v[238:241], v[16:19]
	s_setprio 0
	s_setprio 1
	v_mfma_f32_16x16x32_bf16 v[44:47], v[154:157], v[170:173], v[44:47]
	v_mfma_f32_16x16x32_bf16 v[40:43], v[162:165], v[170:173], v[40:43]
	v_mfma_f32_16x16x32_bf16 v[28:31], v[154:157], v[178:181], v[28:31]
	v_mfma_f32_16x16x32_bf16 v[24:27], v[162:165], v[178:181], v[24:27]
	v_mfma_f32_16x16x32_bf16 v[12:15], v[154:157], v[192:195], v[12:15]
	v_mfma_f32_16x16x32_bf16 v[8:11], v[162:165], v[192:195], v[8:11]
	v_mfma_f32_16x16x32_bf16 v[4:7], v[154:157], v[234:237], v[4:7]
	v_mfma_f32_16x16x32_bf16 v[0:3], v[162:165], v[234:237], v[0:3]
	v_mfma_f32_16x16x32_bf16 v[44:47], v[158:161], v[174:177], v[44:47]
	v_mfma_f32_16x16x32_bf16 v[40:43], v[166:169], v[174:177], v[40:43]
	v_mfma_f32_16x16x32_bf16 v[28:31], v[158:161], v[182:185], v[28:31]
	v_mfma_f32_16x16x32_bf16 v[24:27], v[166:169], v[182:185], v[24:27]
	v_mfma_f32_16x16x32_bf16 v[12:15], v[158:161], v[230:233], v[12:15]
	v_mfma_f32_16x16x32_bf16 v[8:11], v[166:169], v[230:233], v[8:11]
	v_mfma_f32_16x16x32_bf16 v[4:7], v[158:161], v[238:241], v[4:7]
	v_mfma_f32_16x16x32_bf16 v[0:3], v[166:169], v[238:241], v[0:3]
	s_setprio 0
	s_barrier
	v_add_u32_e32 v150, s67, v136
	v_add_u32_e32 v166, s66, v136
	ds_read_b128 v[138:141], v150
	ds_read_b128 v[142:145], v150 offset:1024
	ds_read_b128 v[146:149], v150 offset:2048
	ds_read_b128 v[150:153], v150 offset:3072
	ds_read_b128 v[154:157], v166
	ds_read_b128 v[158:161], v166 offset:1024
	ds_read_b128 v[162:165], v166 offset:2048
	ds_read_b128 v[166:169], v166 offset:3072
	s_mov_b32 m0, s53
	v_lshl_add_u64 v[246:247], s[38:39], 0, v[132:133]
	ds_read_b128 v[170:173], v137 offset:32768
	ds_read_b128 v[174:177], v137 offset:33792
	ds_read_b128 v[178:181], v137 offset:34816
	ds_read_b128 v[182:185], v137 offset:35840
	ds_read_b128 v[192:195], v137 offset:36864
	ds_read_b128 v[230:233], v137 offset:37888
	ds_read_b128 v[234:237], v137 offset:38912
	ds_read_b128 v[238:241], v137 offset:39936
	global_load_lds_dwordx4 v[246:247], off
	s_mov_b32 m0, s54
	v_lshl_add_u64 v[246:247], s[38:39], 0, v[130:131]
	global_load_lds_dwordx4 v[246:247], off
	s_waitcnt vmcnt(8)
	s_waitcnt lgkmcnt(0)
	s_barrier
	s_setprio 1
	s_waitcnt lgkmcnt(0)
	v_mfma_f32_16x16x32_bf16 v[124:127], v[138:141], v[170:173], v[124:127]
	v_mfma_f32_16x16x32_bf16 v[120:123], v[146:149], v[170:173], v[120:123]
	v_mfma_f32_16x16x32_bf16 v[116:119], v[138:141], v[178:181], v[116:119]
	v_mfma_f32_16x16x32_bf16 v[112:115], v[146:149], v[178:181], v[112:115]
	v_mfma_f32_16x16x32_bf16 v[100:103], v[138:141], v[192:195], v[100:103]
	v_mfma_f32_16x16x32_bf16 v[96:99], v[146:149], v[192:195], v[96:99]
	v_mfma_f32_16x16x32_bf16 v[84:87], v[138:141], v[234:237], v[84:87]
	v_mfma_f32_16x16x32_bf16 v[80:83], v[146:149], v[234:237], v[80:83]
	v_mfma_f32_16x16x32_bf16 v[124:127], v[142:145], v[174:177], v[124:127]
	v_mfma_f32_16x16x32_bf16 v[120:123], v[150:153], v[174:177], v[120:123]
	v_mfma_f32_16x16x32_bf16 v[116:119], v[142:145], v[182:185], v[116:119]
	v_mfma_f32_16x16x32_bf16 v[112:115], v[150:153], v[182:185], v[112:115]
	v_mfma_f32_16x16x32_bf16 v[100:103], v[142:145], v[230:233], v[100:103]
	v_mfma_f32_16x16x32_bf16 v[96:99], v[150:153], v[230:233], v[96:99]
	v_mfma_f32_16x16x32_bf16 v[84:87], v[142:145], v[238:241], v[84:87]
	v_mfma_f32_16x16x32_bf16 v[80:83], v[150:153], v[238:241], v[80:83]
	s_setprio 0
	s_setprio 1
	v_mfma_f32_16x16x32_bf16 v[108:111], v[154:157], v[170:173], v[108:111]
	v_mfma_f32_16x16x32_bf16 v[104:107], v[162:165], v[170:173], v[104:107]
	v_mfma_f32_16x16x32_bf16 v[92:95], v[154:157], v[178:181], v[92:95]
	v_mfma_f32_16x16x32_bf16 v[88:91], v[162:165], v[178:181], v[88:91]
	v_mfma_f32_16x16x32_bf16 v[76:79], v[154:157], v[192:195], v[76:79]
	v_mfma_f32_16x16x32_bf16 v[72:75], v[162:165], v[192:195], v[72:75]
	v_mfma_f32_16x16x32_bf16 v[68:71], v[154:157], v[234:237], v[68:71]
	v_mfma_f32_16x16x32_bf16 v[64:67], v[162:165], v[234:237], v[64:67]
	v_mfma_f32_16x16x32_bf16 v[108:111], v[158:161], v[174:177], v[108:111]
	v_mfma_f32_16x16x32_bf16 v[104:107], v[166:169], v[174:177], v[104:107]
	v_mfma_f32_16x16x32_bf16 v[92:95], v[158:161], v[182:185], v[92:95]
	v_mfma_f32_16x16x32_bf16 v[88:91], v[166:169], v[182:185], v[88:91]
	v_mfma_f32_16x16x32_bf16 v[76:79], v[158:161], v[230:233], v[76:79]
	v_mfma_f32_16x16x32_bf16 v[72:75], v[166:169], v[230:233], v[72:75]
	v_mfma_f32_16x16x32_bf16 v[68:71], v[158:161], v[238:241], v[68:71]
	v_mfma_f32_16x16x32_bf16 v[64:67], v[166:169], v[238:241], v[64:67]
	s_setprio 0
	s_barrier
; #define PG8_STAGE(bufoff, gbase, voff) do { _Pragma("unroll") for (int _i = 0; _i < 2; ++_i) \
;         __builtin_amdgcn_global_load_lds((const unsigned*)((const char*)(gbase) + (voff)[_i]), (PG8_LAS unsigned*)(lds + (bufoff) + ldsw + _i * 8192), 16, 0, 0); } while (0)
; #define PG8_LDA(dst, b, h) do { _Pragma("unroll") for (int m = 0; m < 4; ++m) _Pragma("unroll") for (int k = 0; k < 2; ++k) dst[m][k] = *(const PG8_LAS bf16x8*)(lds + PG8_SA(b, h) + aoff + m * 2048 + k * 1024); } while (0)
; #define PG8_MMA(ai, bj, At, Bt) do { __builtin_amdgcn_s_setprio(1); _Pragma("unroll") for (int m = 0; m < 4; ++m) _Pragma("unroll") for (int n = 0; n < 2; ++n) _Pragma("unroll") for (int k = 0; k < 2; ++k) \
;         acc[ai][bj][m][n] = __builtin_amdgcn_mfma_f32_16x16x32_bf16(Bt[n][k], At[m][k], acc[ai][bj][m][n], 0, 0, 0); __builtin_amdgcn_s_setprio(0); } while (0)
; #define PG8_WAIT_V(n) asm volatile("s_waitcnt vmcnt(" #n ")" ::: "memory")
; #define PG8_WAIT_L(n) asm volatile("s_waitcnt lgkmcnt(" #n ")" ::: "memory")
; #define PG8_BAR __builtin_amdgcn_s_barrier()
; #define PG8_SCHED __builtin_amdgcn_sched_barrier(0)
; template <class Epi, class Sched, bool ALIGN_EPI = false, bool SP2 = false>
; __device__ __forceinline__ void gemm_phase(PG8_LAS unsigned char* lds, const Gemm g, const Sched& S, const Epi& E) {
;     ...
;         for (int t = 0; t < nt; t += 2) {
;     ...
;             PG8_LDA(At, 1, 1); PG8_STAGE(PG8_SB(1, 0), b3, voffB); PG8_STAGE(PG8_SB(1, 1), b3 + hstepB, voffB); PG8_STAGE(PG8_SA(1, 0), a3, voffA);
;             PG8_WAIT_V(8); PG8_WAIT_L(0); PG8_BAR; PG8_MMA(1, 0, At, B0); PG8_MMA(1, 1, At, B1); PG8_BAR; PG8_SCHED;
	s_mov_b32 m0, s65
	v_lshl_add_u64 v[186:187], v[186:187], 0, s[94:95]
	ds_read_b128 v[170:173], v137 offset:49152
	ds_read_b128 v[174:177], v137 offset:50176
	ds_read_b128 v[178:181], v137 offset:51200
	ds_read_b128 v[182:185], v137 offset:52224
	ds_read_b128 v[192:195], v137 offset:53248
	ds_read_b128 v[230:233], v137 offset:54272
	ds_read_b128 v[234:237], v137 offset:55296
	ds_read_b128 v[238:241], v137 offset:56320
	global_load_lds_dwordx4 v[186:187], off
	s_mov_b32 m0, s64
	v_lshl_add_u64 v[186:187], v[196:197], 0, s[94:95]
	global_load_lds_dwordx4 v[186:187], off
	s_mov_b32 m0, s73
	v_lshl_add_u64 v[186:187], s[36:37], 0, v[188:189]
	global_load_lds_dwordx4 v[186:187], off
	s_mov_b32 m0, s72
	v_lshl_add_u64 v[186:187], s[36:37], 0, v[128:129]
	global_load_lds_dwordx4 v[186:187], off
	s_mov_b32 m0, s56
	v_lshl_add_u64 v[186:187], v[242:243], 0, s[94:95]
	global_load_lds_dwordx4 v[186:187], off
	s_mov_b32 m0, s57
	v_lshl_add_u64 v[186:187], v[244:245], 0, s[94:95]
	global_load_lds_dwordx4 v[186:187], off
	s_waitcnt vmcnt(8)
	s_waitcnt lgkmcnt(0)
	s_barrier
	s_setprio 1
	s_waitcnt lgkmcnt(0)
	v_mfma_f32_16x16x32_bf16 v[60:63], v[138:141], v[170:173], v[60:63]
	v_mfma_f32_16x16x32_bf16 v[56:59], v[146:149], v[170:173], v[56:59]
	v_mfma_f32_16x16x32_bf16 v[52:55], v[138:141], v[178:181], v[52:55]
	v_mfma_f32_16x16x32_bf16 v[48:51], v[146:149], v[178:181], v[48:51]
	v_mfma_f32_16x16x32_bf16 v[36:39], v[138:141], v[192:195], v[36:39]
	v_mfma_f32_16x16x32_bf16 v[32:35], v[146:149], v[192:195], v[32:35]
	v_mfma_f32_16x16x32_bf16 v[20:23], v[138:141], v[234:237], v[20:23]
	v_mfma_f32_16x16x32_bf16 v[16:19], v[146:149], v[234:237], v[16:19]
	v_mfma_f32_16x16x32_bf16 v[60:63], v[142:145], v[174:177], v[60:63]
	v_mfma_f32_16x16x32_bf16 v[56:59], v[150:153], v[174:177], v[56:59]
	v_mfma_f32_16x16x32_bf16 v[52:55], v[142:145], v[182:185], v[52:55]
	v_mfma_f32_16x16x32_bf16 v[48:51], v[150:153], v[182:185], v[48:51]
	v_mfma_f32_16x16x32_bf16 v[36:39], v[142:145], v[230:233], v[36:39]
	v_mfma_f32_16x16x32_bf16 v[32:35], v[150:153], v[230:233], v[32:35]
	v_mfma_f32_16x16x32_bf16 v[20:23], v[142:145], v[238:241], v[20:23]
	v_mfma_f32_16x16x32_bf16 v[16:19], v[150:153], v[238:241], v[16:19]
	s_setprio 0
	s_setprio 1
	v_mfma_f32_16x16x32_bf16 v[44:47], v[154:157], v[170:173], v[44:47]
	v_mfma_f32_16x16x32_bf16 v[40:43], v[162:165], v[170:173], v[40:43]
	v_mfma_f32_16x16x32_bf16 v[28:31], v[154:157], v[178:181], v[28:31]
	v_mfma_f32_16x16x32_bf16 v[24:27], v[162:165], v[178:181], v[24:27]
	v_mfma_f32_16x16x32_bf16 v[12:15], v[154:157], v[192:195], v[12:15]
	v_mfma_f32_16x16x32_bf16 v[8:11], v[162:165], v[192:195], v[8:11]
	v_mfma_f32_16x16x32_bf16 v[4:7], v[154:157], v[234:237], v[4:7]
	v_mfma_f32_16x16x32_bf16 v[0:3], v[162:165], v[234:237], v[0:3]
	v_mfma_f32_16x16x32_bf16 v[44:47], v[158:161], v[174:177], v[44:47]
	v_mfma_f32_16x16x32_bf16 v[40:43], v[166:169], v[174:177], v[40:43]
	v_mfma_f32_16x16x32_bf16 v[28:31], v[158:161], v[182:185], v[28:31]
	v_mfma_f32_16x16x32_bf16 v[24:27], v[166:169], v[182:185], v[24:27]
	v_mfma_f32_16x16x32_bf16 v[12:15], v[158:161], v[230:233], v[12:15]
	v_mfma_f32_16x16x32_bf16 v[8:11], v[166:169], v[230:233], v[8:11]
	v_mfma_f32_16x16x32_bf16 v[4:7], v[158:161], v[238:241], v[4:7]
	v_mfma_f32_16x16x32_bf16 v[0:3], v[166:169], v[238:241], v[0:3]
	s_setprio 0
	s_barrier
	s_andn2_b64 vcc, exec, s[8:9]
	s_mov_b64 s[36:37], -1
	s_mov_b64 s[8:9], 0
	s_mov_b64 s[38:39], 0x100
	s_cbranch_vccz .LBB0_901
	s_and_b64 vcc, exec, s[20:21]
	s_cbranch_vccz .LBB0_904
	s_barrier

; #define PG8_STAGE(bufoff, gbase, voff) do { _Pragma("unroll") for (int _i = 0; _i < 2; ++_i) \
;         __builtin_amdgcn_global_load_lds((const unsigned*)((const char*)(gbase) + (voff)[_i]), (PG8_LAS unsigned*)(lds + (bufoff) + ldsw + _i * 8192), 16, 0, 0); } while (0)
; #define PG8_LDA(dst, b, h) do { _Pragma("unroll") for (int m = 0; m < 4; ++m) _Pragma("unroll") for (int k = 0; k < 2; ++k) dst[m][k] = *(const PG8_LAS bf16x8*)(lds + PG8_SA(b, h) + aoff + m * 2048 + k * 1024); } while (0)
; #define PG8_LDB(dst, b, h) do { _Pragma("unroll") for (int n = 0; n < 2; ++n) _Pragma("unroll") for (int k = 0; k < 2; ++k) dst[n][k] = *(const PG8_LAS bf16x8*)(lds + PG8_SB(b, h) + boff + n * 2048 + k * 1024); } while (0)
; #define PG8_MMA(ai, bj, At, Bt) do { __builtin_amdgcn_s_setprio(1); _Pragma("unroll") for (int m = 0; m < 4; ++m) _Pragma("unroll") for (int n = 0; n < 2; ++n) _Pragma("unroll") for (int k = 0; k < 2; ++k) \
;         acc[ai][bj][m][n] = __builtin_amdgcn_mfma_f32_16x16x32_bf16(Bt[n][k], At[m][k], acc[ai][bj][m][n], 0, 0, 0); __builtin_amdgcn_s_setprio(0); } while (0)
; #define PG8_WAIT_V(n) asm volatile("s_waitcnt vmcnt(" #n ")" ::: "memory")
; #define PG8_WAIT_L(n) asm volatile("s_waitcnt lgkmcnt(" #n ")" ::: "memory")
; #define PG8_BAR __builtin_amdgcn_s_barrier()
; #define PG8_SCHED __builtin_amdgcn_sched_barrier(0)
; template <class Epi, class Sched, bool ALIGN_EPI = false, bool SP2 = false>
; __device__ __forceinline__ void gemm_phase(PG8_LAS unsigned char* lds, const Gemm g, const Sched& S, const Epi& E) {
;     ...
;         for (int t = 0; t < nt; t += 2) {
;             const bool last = (t == nt - 2);
;             const char* a1 = cA + (size_t)(t + 1) * kstep;
;             const char* a2 = last ? nA : cA + (size_t)(t + 2) * kstep; const char* b2 = last ? nB : cB + (size_t)(t + 2) * kstep;
;             const char* a3 = a2 + kstep; const char* b3 = b2 + kstep;
;             if (last && has_next) S.a_ready(nxt);
;             if constexpr (SP2) {
;             PG8_LDB(B0, 0, 0); PG8_LDB(B1, 0, 1); PG8_SCHED; PG8_LDA(At, 0, 0); PG8_STAGE(PG8_SA(1, 1), a1 + hstepA, voffA);
;             PG8_WAIT_V(8); PG8_WAIT_L(0); PG8_BAR; PG8_MMA(0, 0, At, B0); PG8_MMA(0, 1, At, B1); PG8_BAR; PG8_SCHED;
;             PG8_LDA(At, 0, 1); PG8_STAGE(PG8_SB(0, 0), b2, voffB); PG8_STAGE(PG8_SB(0, 1), b2 + hstepB, voffB); PG8_STAGE(PG8_SA(0, 0), a2, voffA);
.LBB0_1642:
	s_add_i32 s74, s28, 2
	s_add_u32 s75, s26, 0x80
	s_addc_u32 s29, s27, 0
	s_add_i32 s78, 0, 0x10000
	s_cmp_eq_u32 s54, s28
	s_cselect_b32 s29, s9, s29
	s_cselect_b32 s28, s8, s75
	s_cselect_b32 s77, s25, s73
	s_cselect_b32 s76, s24, s72
	s_add_i32 s75, 0, 0x14000
	v_add_u32_e32 v150, s78, v148
	v_add_u32_e32 v166, s75, v148
	ds_read_b128 v[128:131], v150
	ds_read_b128 v[138:141], v150 offset:1024
	ds_read_b128 v[142:145], v150 offset:2048
	ds_read_b128 v[150:153], v150 offset:3072
	ds_read_b128 v[154:157], v166
	ds_read_b128 v[158:161], v166 offset:1024
	ds_read_b128 v[162:165], v166 offset:2048
	ds_read_b128 v[166:169], v166 offset:3072
	v_lshl_add_u64 v[186:187], s[26:27], 0, v[134:135]
	s_add_i32 m0, s36, 0xc000
	ds_read_b128 v[170:173], v149
	ds_read_b128 v[174:177], v149 offset:1024
	ds_read_b128 v[178:181], v149 offset:2048
	ds_read_b128 v[182:185], v149 offset:3072
	ds_read_b128 v[192:195], v149 offset:4096
	ds_read_b128 v[230:233], v149 offset:5120
	ds_read_b128 v[234:237], v149 offset:6144
	ds_read_b128 v[238:241], v149 offset:7168
	global_load_lds_dwordx4 v[186:187], off
	s_add_i32 m0, s36, 0xe000
	v_lshl_add_u64 v[186:187], s[26:27], 0, v[136:137]
	global_load_lds_dwordx4 v[186:187], off
	s_waitcnt vmcnt(8)
	s_waitcnt lgkmcnt(0)
	s_barrier
	s_setprio 1
	s_waitcnt lgkmcnt(0)
	v_mfma_f32_16x16x32_bf16 v[124:127], v[128:131], v[170:173], v[124:127]
	v_mfma_f32_16x16x32_bf16 v[96:99], v[142:145], v[170:173], v[96:99]
	v_mfma_f32_16x16x32_bf16 v[120:123], v[128:131], v[178:181], v[120:123]
	v_mfma_f32_16x16x32_bf16 v[92:95], v[142:145], v[178:181], v[92:95]
	v_mfma_f32_16x16x32_bf16 v[116:119], v[128:131], v[192:195], v[116:119]
	v_mfma_f32_16x16x32_bf16 v[88:91], v[142:145], v[192:195], v[88:91]
	v_mfma_f32_16x16x32_bf16 v[112:115], v[128:131], v[234:237], v[112:115]
	v_mfma_f32_16x16x32_bf16 v[80:83], v[142:145], v[234:237], v[80:83]
	v_mfma_f32_16x16x32_bf16 v[124:127], v[138:141], v[174:177], v[124:127]
	v_mfma_f32_16x16x32_bf16 v[96:99], v[150:153], v[174:177], v[96:99]
	v_mfma_f32_16x16x32_bf16 v[120:123], v[138:141], v[182:185], v[120:123]
	v_mfma_f32_16x16x32_bf16 v[92:95], v[150:153], v[182:185], v[92:95]
	v_mfma_f32_16x16x32_bf16 v[116:119], v[138:141], v[230:233], v[116:119]
	v_mfma_f32_16x16x32_bf16 v[88:91], v[150:153], v[230:233], v[88:91]
	v_mfma_f32_16x16x32_bf16 v[112:115], v[138:141], v[238:241], v[112:115]
	v_mfma_f32_16x16x32_bf16 v[80:83], v[150:153], v[238:241], v[80:83]
	s_setprio 0
	s_setprio 1
	v_mfma_f32_16x16x32_bf16 v[72:75], v[154:157], v[170:173], v[72:75]
	v_mfma_f32_16x16x32_bf16 v[44:47], v[162:165], v[170:173], v[44:47]
	v_mfma_f32_16x16x32_bf16 v[64:67], v[154:157], v[178:181], v[64:67]
	v_mfma_f32_16x16x32_bf16 v[36:39], v[162:165], v[178:181], v[36:39]
	v_mfma_f32_16x16x32_bf16 v[56:59], v[154:157], v[192:195], v[56:59]
	v_mfma_f32_16x16x32_bf16 v[28:31], v[162:165], v[192:195], v[28:31]
	v_mfma_f32_16x16x32_bf16 v[48:51], v[154:157], v[234:237], v[48:51]
	v_mfma_f32_16x16x32_bf16 v[20:23], v[162:165], v[234:237], v[20:23]
	v_mfma_f32_16x16x32_bf16 v[72:75], v[158:161], v[174:177], v[72:75]
	v_mfma_f32_16x16x32_bf16 v[44:47], v[166:169], v[174:177], v[44:47]
	v_mfma_f32_16x16x32_bf16 v[64:67], v[158:161], v[182:185], v[64:67]
	v_mfma_f32_16x16x32_bf16 v[36:39], v[166:169], v[182:185], v[36:39]
	v_mfma_f32_16x16x32_bf16 v[56:59], v[158:161], v[230:233], v[56:59]
	v_mfma_f32_16x16x32_bf16 v[28:31], v[166:169], v[230:233], v[28:31]
	v_mfma_f32_16x16x32_bf16 v[48:51], v[158:161], v[238:241], v[48:51]
	v_mfma_f32_16x16x32_bf16 v[20:23], v[166:169], v[238:241], v[20:23]
	s_setprio 0
	s_barrier
	s_add_i32 s78, s78, s30
	v_lshl_add_u64 v[186:187], s[76:77], 0, v[188:189]
	s_mov_b32 m0, s78
	ds_read_b128 v[170:173], v149 offset:16384
	ds_read_b128 v[174:177], v149 offset:17408
	ds_read_b128 v[178:181], v149 offset:18432
	ds_read_b128 v[182:185], v149 offset:19456
	ds_read_b128 v[192:195], v149 offset:20480
	ds_read_b128 v[230:233], v149 offset:21504
	ds_read_b128 v[234:237], v149 offset:22528
	ds_read_b128 v[238:241], v149 offset:23552
	global_load_lds_dwordx4 v[186:187], off
	s_add_i32 m0, s78, 0x2000
	v_lshl_add_u64 v[196:197], s[76:77], 0, v[132:133]
	s_add_u32 s76, s76, s44
	s_addc_u32 s77, s77, 0
	s_add_i32 s75, s75, s30
	global_load_lds_dwordx4 v[196:197], off
	v_lshl_add_u64 v[242:243], s[76:77], 0, v[188:189]
	s_mov_b32 m0, s75
	v_lshl_add_u64 v[244:245], s[76:77], 0, v[132:133]
	global_load_lds_dwordx4 v[242:243], off
	s_add_i32 m0, s75, 0x2000
	v_lshl_add_u64 v[246:247], s[28:29], 0, v[188:189]
	global_load_lds_dwordx4 v[244:245], off
	s_mov_b32 m0, s36
	v_lshl_add_u64 v[248:249], s[28:29], 0, v[132:133]
	global_load_lds_dwordx4 v[246:247], off
	s_mov_b32 m0, s37
	s_nop 0
	global_load_lds_dwordx4 v[248:249], off
	s_waitcnt vmcnt(8)
	s_waitcnt lgkmcnt(0)
	s_barrier
; #define PG8_STAGE(bufoff, gbase, voff) do { _Pragma("unroll") for (int _i = 0; _i < 2; ++_i) \
;         __builtin_amdgcn_global_load_lds((const unsigned*)((const char*)(gbase) + (voff)[_i]), (PG8_LAS unsigned*)(lds + (bufoff) + ldsw + _i * 8192), 16, 0, 0); } while (0)
; #define PG8_LDA(dst, b, h) do { _Pragma("unroll") for (int m = 0; m < 4; ++m) _Pragma("unroll") for (int k = 0; k < 2; ++k) dst[m][k] = *(const PG8_LAS bf16x8*)(lds + PG8_SA(b, h) + aoff + m * 2048 + k * 1024); } while (0)
; #define PG8_LDB(dst, b, h) do { _Pragma("unroll") for (int n = 0; n < 2; ++n) _Pragma("unroll") for (int k = 0; k < 2; ++k) dst[n][k] = *(const PG8_LAS bf16x8*)(lds + PG8_SB(b, h) + boff + n * 2048 + k * 1024); } while (0)
; #define PG8_MMA(ai, bj, At, Bt) do { __builtin_amdgcn_s_setprio(1); _Pragma("unroll") for (int m = 0; m < 4; ++m) _Pragma("unroll") for (int n = 0; n < 2; ++n) _Pragma("unroll") for (int k = 0; k < 2; ++k) \
;         acc[ai][bj][m][n] = __builtin_amdgcn_mfma_f32_16x16x32_bf16(Bt[n][k], At[m][k], acc[ai][bj][m][n], 0, 0, 0); __builtin_amdgcn_s_setprio(0); } while (0)
; #define PG8_WAIT_V(n) asm volatile("s_waitcnt vmcnt(" #n ")" ::: "memory")
; #define PG8_WAIT_L(n) asm volatile("s_waitcnt lgkmcnt(" #n ")" ::: "memory")
; #define PG8_BAR __builtin_amdgcn_s_barrier()
; #define PG8_SCHED __builtin_amdgcn_sched_barrier(0)
; template <class Epi, class Sched, bool ALIGN_EPI = false, bool SP2 = false>
; __device__ __forceinline__ void gemm_phase(PG8_LAS unsigned char* lds, const Gemm g, const Sched& S, const Epi& E) {
;     ...
;             PG8_WAIT_V(8); PG8_WAIT_L(0); PG8_BAR; PG8_MMA(1, 0, At, B0); PG8_MMA(1, 1, At, B1); PG8_BAR; PG8_SCHED;
;             PG8_LDB(B0, 1, 0); PG8_LDB(B1, 1, 1); PG8_SCHED; PG8_LDA(At, 1, 0); PG8_STAGE(PG8_SA(0, 1), a2 + hstepA, voffA);
;             PG8_WAIT_V(8); PG8_WAIT_L(0); PG8_BAR; PG8_MMA(0, 0, At, B0); PG8_MMA(0, 1, At, B1); PG8_BAR; PG8_SCHED;
	s_setprio 1
	s_waitcnt lgkmcnt(0)
	v_mfma_f32_16x16x32_bf16 v[108:111], v[128:131], v[170:173], v[108:111]
	v_mfma_f32_16x16x32_bf16 v[76:79], v[142:145], v[170:173], v[76:79]
	v_mfma_f32_16x16x32_bf16 v[104:107], v[128:131], v[178:181], v[104:107]
	v_mfma_f32_16x16x32_bf16 v[68:71], v[142:145], v[178:181], v[68:71]
	v_mfma_f32_16x16x32_bf16 v[100:103], v[128:131], v[192:195], v[100:103]
	v_mfma_f32_16x16x32_bf16 v[60:63], v[142:145], v[192:195], v[60:63]
	v_mfma_f32_16x16x32_bf16 v[84:87], v[128:131], v[234:237], v[84:87]
	v_mfma_f32_16x16x32_bf16 v[52:55], v[142:145], v[234:237], v[52:55]
	v_mfma_f32_16x16x32_bf16 v[108:111], v[138:141], v[174:177], v[108:111]
	v_mfma_f32_16x16x32_bf16 v[76:79], v[150:153], v[174:177], v[76:79]
	v_mfma_f32_16x16x32_bf16 v[104:107], v[138:141], v[182:185], v[104:107]
	v_mfma_f32_16x16x32_bf16 v[68:71], v[150:153], v[182:185], v[68:71]
	v_mfma_f32_16x16x32_bf16 v[100:103], v[138:141], v[230:233], v[100:103]
	v_mfma_f32_16x16x32_bf16 v[60:63], v[150:153], v[230:233], v[60:63]
	v_mfma_f32_16x16x32_bf16 v[84:87], v[138:141], v[238:241], v[84:87]
	v_mfma_f32_16x16x32_bf16 v[52:55], v[150:153], v[238:241], v[52:55]
	s_setprio 0
	s_setprio 1
	v_mfma_f32_16x16x32_bf16 v[40:43], v[154:157], v[170:173], v[40:43]
	v_mfma_f32_16x16x32_bf16 v[12:15], v[162:165], v[170:173], v[12:15]
	v_mfma_f32_16x16x32_bf16 v[32:35], v[154:157], v[178:181], v[32:35]
	v_mfma_f32_16x16x32_bf16 v[8:11], v[162:165], v[178:181], v[8:11]
	v_mfma_f32_16x16x32_bf16 v[24:27], v[154:157], v[192:195], v[24:27]
	v_mfma_f32_16x16x32_bf16 v[4:7], v[162:165], v[192:195], v[4:7]
	v_mfma_f32_16x16x32_bf16 v[16:19], v[154:157], v[234:237], v[16:19]
	v_mfma_f32_16x16x32_bf16 v[0:3], v[162:165], v[234:237], v[0:3]
	v_mfma_f32_16x16x32_bf16 v[40:43], v[158:161], v[174:177], v[40:43]
	v_mfma_f32_16x16x32_bf16 v[12:15], v[166:169], v[174:177], v[12:15]
	v_mfma_f32_16x16x32_bf16 v[32:35], v[158:161], v[182:185], v[32:35]
	v_mfma_f32_16x16x32_bf16 v[8:11], v[166:169], v[182:185], v[8:11]
	v_mfma_f32_16x16x32_bf16 v[24:27], v[158:161], v[230:233], v[24:27]
	v_mfma_f32_16x16x32_bf16 v[4:7], v[166:169], v[230:233], v[4:7]
	v_mfma_f32_16x16x32_bf16 v[16:19], v[158:161], v[238:241], v[16:19]
	v_mfma_f32_16x16x32_bf16 v[0:3], v[166:169], v[238:241], v[0:3]
	s_setprio 0
	s_barrier
	s_add_i32 s75, 0, 0x18000
	s_add_i32 s76, 0, 0x1c000
	v_add_u32_e32 v150, s75, v148
	v_add_u32_e32 v166, s76, v148
	ds_read_b128 v[128:131], v150
	ds_read_b128 v[138:141], v150 offset:1024
	ds_read_b128 v[142:145], v150 offset:2048
	ds_read_b128 v[150:153], v150 offset:3072
	ds_read_b128 v[154:157], v166
	ds_read_b128 v[158:161], v166 offset:1024
	ds_read_b128 v[162:165], v166 offset:2048
	ds_read_b128 v[166:169], v166 offset:3072
	s_add_u32 s28, s28, s44
	s_addc_u32 s29, s29, 0
	s_mov_b32 m0, s46
	v_lshl_add_u64 v[250:251], s[28:29], 0, v[188:189]
	ds_read_b128 v[170:173], v149 offset:32768
	ds_read_b128 v[174:177], v149 offset:33792
	ds_read_b128 v[178:181], v149 offset:34816
	ds_read_b128 v[182:185], v149 offset:35840
	ds_read_b128 v[192:195], v149 offset:36864
	ds_read_b128 v[230:233], v149 offset:37888
	ds_read_b128 v[234:237], v149 offset:38912
	ds_read_b128 v[238:241], v149 offset:39936
	global_load_lds_dwordx4 v[250:251], off
	s_mov_b32 m0, s47
	v_lshl_add_u64 v[250:251], s[28:29], 0, v[132:133]
	global_load_lds_dwordx4 v[250:251], off
	s_waitcnt vmcnt(8)
	s_waitcnt lgkmcnt(0)
	s_barrier
	s_setprio 1
	s_waitcnt lgkmcnt(0)
	v_mfma_f32_16x16x32_bf16 v[124:127], v[128:131], v[170:173], v[124:127]
	v_mfma_f32_16x16x32_bf16 v[96:99], v[142:145], v[170:173], v[96:99]
	v_mfma_f32_16x16x32_bf16 v[120:123], v[128:131], v[178:181], v[120:123]
	v_mfma_f32_16x16x32_bf16 v[92:95], v[142:145], v[178:181], v[92:95]
	v_mfma_f32_16x16x32_bf16 v[116:119], v[128:131], v[192:195], v[116:119]
	v_mfma_f32_16x16x32_bf16 v[88:91], v[142:145], v[192:195], v[88:91]
	v_mfma_f32_16x16x32_bf16 v[112:115], v[128:131], v[234:237], v[112:115]
	v_mfma_f32_16x16x32_bf16 v[80:83], v[142:145], v[234:237], v[80:83]
	v_mfma_f32_16x16x32_bf16 v[124:127], v[138:141], v[174:177], v[124:127]
	v_mfma_f32_16x16x32_bf16 v[96:99], v[150:153], v[174:177], v[96:99]
	v_mfma_f32_16x16x32_bf16 v[120:123], v[138:141], v[182:185], v[120:123]
	v_mfma_f32_16x16x32_bf16 v[92:95], v[150:153], v[182:185], v[92:95]
	v_mfma_f32_16x16x32_bf16 v[116:119], v[138:141], v[230:233], v[116:119]
	v_mfma_f32_16x16x32_bf16 v[88:91], v[150:153], v[230:233], v[88:91]
	v_mfma_f32_16x16x32_bf16 v[112:115], v[138:141], v[238:241], v[112:115]
	v_mfma_f32_16x16x32_bf16 v[80:83], v[150:153], v[238:241], v[80:83]
	s_setprio 0
	s_setprio 1
	v_mfma_f32_16x16x32_bf16 v[72:75], v[154:157], v[170:173], v[72:75]
	v_mfma_f32_16x16x32_bf16 v[44:47], v[162:165], v[170:173], v[44:47]
	v_mfma_f32_16x16x32_bf16 v[64:67], v[154:157], v[178:181], v[64:67]
	v_mfma_f32_16x16x32_bf16 v[36:39], v[162:165], v[178:181], v[36:39]
	v_mfma_f32_16x16x32_bf16 v[56:59], v[154:157], v[192:195], v[56:59]
	v_mfma_f32_16x16x32_bf16 v[28:31], v[162:165], v[192:195], v[28:31]
	v_mfma_f32_16x16x32_bf16 v[48:51], v[154:157], v[234:237], v[48:51]
	v_mfma_f32_16x16x32_bf16 v[20:23], v[162:165], v[234:237], v[20:23]
	v_mfma_f32_16x16x32_bf16 v[72:75], v[158:161], v[174:177], v[72:75]
	v_mfma_f32_16x16x32_bf16 v[44:47], v[166:169], v[174:177], v[44:47]
	v_mfma_f32_16x16x32_bf16 v[64:67], v[158:161], v[182:185], v[64:67]
	v_mfma_f32_16x16x32_bf16 v[36:39], v[166:169], v[182:185], v[36:39]
	v_mfma_f32_16x16x32_bf16 v[56:59], v[158:161], v[230:233], v[56:59]
	v_mfma_f32_16x16x32_bf16 v[28:31], v[166:169], v[230:233], v[28:31]
	v_mfma_f32_16x16x32_bf16 v[48:51], v[158:161], v[238:241], v[48:51]
	v_mfma_f32_16x16x32_bf16 v[20:23], v[166:169], v[238:241], v[20:23]
	s_setprio 0
	s_barrier
; #define PG8_STAGE(bufoff, gbase, voff) do { _Pragma("unroll") for (int _i = 0; _i < 2; ++_i) \
;         __builtin_amdgcn_global_load_lds((const unsigned*)((const char*)(gbase) + (voff)[_i]), (PG8_LAS unsigned*)(lds + (bufoff) + ldsw + _i * 8192), 16, 0, 0); } while (0)
; #define PG8_LDA(dst, b, h) do { _Pragma("unroll") for (int m = 0; m < 4; ++m) _Pragma("unroll") for (int k = 0; k < 2; ++k) dst[m][k] = *(const PG8_LAS bf16x8*)(lds + PG8_SA(b, h) + aoff + m * 2048 + k * 1024); } while (0)
; #define PG8_MMA(ai, bj, At, Bt) do { __builtin_amdgcn_s_setprio(1); _Pragma("unroll") for (int m = 0; m < 4; ++m) _Pragma("unroll") for (int n = 0; n < 2; ++n) _Pragma("unroll") for (int k = 0; k < 2; ++k) \
;         acc[ai][bj][m][n] = __builtin_amdgcn_mfma_f32_16x16x32_bf16(Bt[n][k], At[m][k], acc[ai][bj][m][n], 0, 0, 0); __builtin_amdgcn_s_setprio(0); } while (0)
; #define PG8_WAIT_V(n) asm volatile("s_waitcnt vmcnt(" #n ")" ::: "memory")
; #define PG8_WAIT_L(n) asm volatile("s_waitcnt lgkmcnt(" #n ")" ::: "memory")
; #define PG8_BAR __builtin_amdgcn_s_barrier()
; #define PG8_SCHED __builtin_amdgcn_sched_barrier(0)
; template <class Epi, class Sched, bool ALIGN_EPI = false, bool SP2 = false>
; __device__ __forceinline__ void gemm_phase(PG8_LAS unsigned char* lds, const Gemm g, const Sched& S, const Epi& E) {
;     ...
;             PG8_LDA(At, 1, 1); PG8_STAGE(PG8_SB(1, 0), b3, voffB); PG8_STAGE(PG8_SB(1, 1), b3 + hstepB, voffB); PG8_STAGE(PG8_SA(1, 0), a3, voffA);
;             PG8_WAIT_V(8); PG8_WAIT_L(0); PG8_BAR; PG8_MMA(1, 0, At, B0); PG8_MMA(1, 1, At, B1); PG8_BAR; PG8_SCHED;
;     ...
;         if constexpr (ALIGN_EPI) { if (wr == 0) PG8_BAR; }
	s_add_i32 s28, s75, s30
	v_lshl_add_u64 v[186:187], v[186:187], 0, s[94:95]
	s_mov_b32 m0, s28
	ds_read_b128 v[170:173], v149 offset:49152
	ds_read_b128 v[174:177], v149 offset:50176
	ds_read_b128 v[178:181], v149 offset:51200
	ds_read_b128 v[182:185], v149 offset:52224
	ds_read_b128 v[192:195], v149 offset:53248
	ds_read_b128 v[230:233], v149 offset:54272
	ds_read_b128 v[234:237], v149 offset:55296
	ds_read_b128 v[238:241], v149 offset:56320
	global_load_lds_dwordx4 v[186:187], off
	v_lshl_add_u64 v[186:187], v[196:197], 0, s[94:95]
	s_add_i32 m0, s28, 0x2000
	s_add_i32 s28, s76, s30
	global_load_lds_dwordx4 v[186:187], off
	s_mov_b32 m0, s28
	v_lshl_add_u64 v[186:187], v[242:243], 0, s[94:95]
	global_load_lds_dwordx4 v[186:187], off
	s_add_i32 m0, s28, 0x2000
	v_lshl_add_u64 v[186:187], v[244:245], 0, s[94:95]
	global_load_lds_dwordx4 v[186:187], off
	s_mov_b32 m0, s62
	v_lshl_add_u64 v[186:187], v[246:247], 0, s[94:95]
	global_load_lds_dwordx4 v[186:187], off
	s_mov_b32 m0, s63
	v_lshl_add_u64 v[186:187], v[248:249], 0, s[94:95]
	global_load_lds_dwordx4 v[186:187], off
	s_waitcnt vmcnt(8)
	s_waitcnt lgkmcnt(0)
	s_barrier
	s_setprio 1
	s_waitcnt lgkmcnt(0)
	v_mfma_f32_16x16x32_bf16 v[108:111], v[128:131], v[170:173], v[108:111]
	v_mfma_f32_16x16x32_bf16 v[76:79], v[142:145], v[170:173], v[76:79]
	v_mfma_f32_16x16x32_bf16 v[104:107], v[128:131], v[178:181], v[104:107]
	v_mfma_f32_16x16x32_bf16 v[68:71], v[142:145], v[178:181], v[68:71]
	v_mfma_f32_16x16x32_bf16 v[100:103], v[128:131], v[192:195], v[100:103]
	v_mfma_f32_16x16x32_bf16 v[60:63], v[142:145], v[192:195], v[60:63]
	v_mfma_f32_16x16x32_bf16 v[84:87], v[128:131], v[234:237], v[84:87]
	v_mfma_f32_16x16x32_bf16 v[52:55], v[142:145], v[234:237], v[52:55]
	v_mfma_f32_16x16x32_bf16 v[108:111], v[138:141], v[174:177], v[108:111]
	v_mfma_f32_16x16x32_bf16 v[76:79], v[150:153], v[174:177], v[76:79]
	v_mfma_f32_16x16x32_bf16 v[104:107], v[138:141], v[182:185], v[104:107]
	v_mfma_f32_16x16x32_bf16 v[68:71], v[150:153], v[182:185], v[68:71]
	v_mfma_f32_16x16x32_bf16 v[100:103], v[138:141], v[230:233], v[100:103]
	v_mfma_f32_16x16x32_bf16 v[60:63], v[150:153], v[230:233], v[60:63]
	v_mfma_f32_16x16x32_bf16 v[84:87], v[138:141], v[238:241], v[84:87]
	v_mfma_f32_16x16x32_bf16 v[52:55], v[150:153], v[238:241], v[52:55]
	s_setprio 0
	s_setprio 1
	v_mfma_f32_16x16x32_bf16 v[40:43], v[154:157], v[170:173], v[40:43]
	v_mfma_f32_16x16x32_bf16 v[12:15], v[162:165], v[170:173], v[12:15]
	v_mfma_f32_16x16x32_bf16 v[32:35], v[154:157], v[178:181], v[32:35]
	v_mfma_f32_16x16x32_bf16 v[8:11], v[162:165], v[178:181], v[8:11]
	v_mfma_f32_16x16x32_bf16 v[24:27], v[154:157], v[192:195], v[24:27]
	v_mfma_f32_16x16x32_bf16 v[4:7], v[162:165], v[192:195], v[4:7]
	v_mfma_f32_16x16x32_bf16 v[16:19], v[154:157], v[234:237], v[16:19]
	v_mfma_f32_16x16x32_bf16 v[0:3], v[162:165], v[234:237], v[0:3]
	v_mfma_f32_16x16x32_bf16 v[40:43], v[158:161], v[174:177], v[40:43]
	v_mfma_f32_16x16x32_bf16 v[12:15], v[166:169], v[174:177], v[12:15]
	v_mfma_f32_16x16x32_bf16 v[32:35], v[158:161], v[182:185], v[32:35]
	v_mfma_f32_16x16x32_bf16 v[8:11], v[166:169], v[182:185], v[8:11]
	v_mfma_f32_16x16x32_bf16 v[24:27], v[158:161], v[230:233], v[24:27]
	v_mfma_f32_16x16x32_bf16 v[4:7], v[166:169], v[230:233], v[4:7]
	v_mfma_f32_16x16x32_bf16 v[16:19], v[158:161], v[238:241], v[16:19]
	v_mfma_f32_16x16x32_bf16 v[0:3], v[166:169], v[238:241], v[0:3]
	s_setprio 0
	s_barrier
	s_add_u32 s26, s26, 0x100
	s_addc_u32 s27, s27, 0
	s_add_u32 s72, s72, 0x100
	s_addc_u32 s73, s73, 0
	s_cmp_ge_u32 s74, s52
	s_mov_b32 s28, s74
	s_cbranch_scc0 .LBB0_1642
	s_and_b64 vcc, exec, s[14:15]
	s_cbranch_vccz .LBB0_1645
	s_barrier

; #define PG8_STAGE(bufoff, gbase, voff) do { _Pragma("unroll") for (int _i = 0; _i < 2; ++_i) \
;         __builtin_amdgcn_global_load_lds((const unsigned*)((const char*)(gbase) + (voff)[_i]), (PG8_LAS unsigned*)(lds + (bufoff) + ldsw + _i * 8192), 16, 0, 0); } while (0)
; #define PG8_LDA(dst, b, h) do { _Pragma("unroll") for (int m = 0; m < 4; ++m) _Pragma("unroll") for (int k = 0; k < 2; ++k) dst[m][k] = *(const PG8_LAS bf16x8*)(lds + PG8_SA(b, h) + aoff + m * 2048 + k * 1024); } while (0)
; #define PG8_LDB(dst, b, h) do { _Pragma("unroll") for (int n = 0; n < 2; ++n) _Pragma("unroll") for (int k = 0; k < 2; ++k) dst[n][k] = *(const PG8_LAS bf16x8*)(lds + PG8_SB(b, h) + boff + n * 2048 + k * 1024); } while (0)
; #define PG8_MMA(ai, bj, At, Bt) do { __builtin_amdgcn_s_setprio(1); _Pragma("unroll") for (int m = 0; m < 4; ++m) _Pragma("unroll") for (int n = 0; n < 2; ++n) _Pragma("unroll") for (int k = 0; k < 2; ++k) \
;         acc[ai][bj][m][n] = __builtin_amdgcn_mfma_f32_16x16x32_bf16(Bt[n][k], At[m][k], acc[ai][bj][m][n], 0, 0, 0); __builtin_amdgcn_s_setprio(0); } while (0)
; #define PG8_WAIT_V(n) asm volatile("s_waitcnt vmcnt(" #n ")" ::: "memory")
; #define PG8_WAIT_L(n) asm volatile("s_waitcnt lgkmcnt(" #n ")" ::: "memory")
; #define PG8_BAR __builtin_amdgcn_s_barrier()
; #define PG8_SCHED __builtin_amdgcn_sched_barrier(0)
; template <class Epi, class Sched, bool ALIGN_EPI = false, bool SP2 = false>
; __device__ __forceinline__ void gemm_phase(PG8_LAS unsigned char* lds, const Gemm g, const Sched& S, const Epi& E) {
;     ...
;         for (int t = 0; t < nt; t += 2) {
;             const bool last = (t == nt - 2);
;             const char* a1 = cA + (size_t)(t + 1) * kstep;
;             const char* a2 = last ? nA : cA + (size_t)(t + 2) * kstep; const char* b2 = last ? nB : cB + (size_t)(t + 2) * kstep;
;             const char* a3 = a2 + kstep; const char* b3 = b2 + kstep;
;             if (last && has_next) S.a_ready(nxt);
;             if constexpr (SP2) {
;             PG8_LDB(B0, 0, 0); PG8_LDB(B1, 0, 1); PG8_SCHED; PG8_LDA(At, 0, 0); PG8_STAGE(PG8_SA(1, 1), a1 + hstepA, voffA);
;             PG8_WAIT_V(8); PG8_WAIT_L(0); PG8_BAR; PG8_MMA(0, 0, At, B0); PG8_MMA(0, 1, At, B1); PG8_BAR; PG8_SCHED;
;             PG8_LDA(At, 0, 1); PG8_STAGE(PG8_SB(0, 0), b2, voffB); PG8_STAGE(PG8_SB(0, 1), b2 + hstepB, voffB); PG8_STAGE(PG8_SA(0, 0), a2, voffA);
.LBB0_1800:
	s_add_u32 s10, s8, 0xfffc0080
	s_addc_u32 s11, s9, -1
	s_add_i32 s71, 0, 0x10000
	s_cmp_eq_u32 s70, 12
	s_cselect_b32 s45, s13, s11
	s_cselect_b32 s44, s15, s10
	s_cselect_b32 s11, s35, s47
	s_cselect_b32 s10, s37, s46
	s_add_i32 s74, 0, 0x14000
	v_add_u32_e32 v140, s71, v229
	v_add_u32_e32 v156, s74, v229
	ds_read_b128 v[128:131], v140
	ds_read_b128 v[132:135], v140 offset:1024
	ds_read_b128 v[136:139], v140 offset:2048
	ds_read_b128 v[140:143], v140 offset:3072
	ds_read_b128 v[144:147], v156
	ds_read_b128 v[148:151], v156 offset:1024
	ds_read_b128 v[152:155], v156 offset:2048
	ds_read_b128 v[156:159], v156 offset:3072
	v_lshl_add_u64 v[186:187], s[8:9], 0, v[174:175]
	s_add_i32 m0, s54, 0xc000
	ds_read_b128 v[160:163], v230
	ds_read_b128 v[164:167], v230 offset:1024
	ds_read_b128 v[178:181], v230 offset:2048
	ds_read_b128 v[182:185], v230 offset:3072
	ds_read_b128 v[192:195], v230 offset:4096
	ds_read_b128 v[232:235], v230 offset:5120
	ds_read_b128 v[236:239], v230 offset:6144
	ds_read_b128 v[240:243], v230 offset:7168
	global_load_lds_dwordx4 v[186:187], off
	s_add_i32 m0, s54, 0xe000
	v_lshl_add_u64 v[186:187], s[8:9], 0, v[176:177]
	global_load_lds_dwordx4 v[186:187], off
	s_waitcnt vmcnt(8)
	s_waitcnt lgkmcnt(0)
	s_barrier
	s_setprio 1
	s_waitcnt lgkmcnt(0)
	v_mfma_f32_16x16x32_bf16 v[124:127], v[128:131], v[160:163], v[124:127]
	v_mfma_f32_16x16x32_bf16 v[60:63], v[136:139], v[160:163], v[60:63]
	v_mfma_f32_16x16x32_bf16 v[120:123], v[128:131], v[178:181], v[120:123]
	v_mfma_f32_16x16x32_bf16 v[56:59], v[136:139], v[178:181], v[56:59]
	v_mfma_f32_16x16x32_bf16 v[108:111], v[128:131], v[192:195], v[108:111]
	v_mfma_f32_16x16x32_bf16 v[44:47], v[136:139], v[192:195], v[44:47]
	v_mfma_f32_16x16x32_bf16 v[100:103], v[128:131], v[236:239], v[100:103]
	v_mfma_f32_16x16x32_bf16 v[36:39], v[136:139], v[236:239], v[36:39]
	v_mfma_f32_16x16x32_bf16 v[124:127], v[132:135], v[164:167], v[124:127]
	v_mfma_f32_16x16x32_bf16 v[60:63], v[140:143], v[164:167], v[60:63]
	v_mfma_f32_16x16x32_bf16 v[120:123], v[132:135], v[182:185], v[120:123]
	v_mfma_f32_16x16x32_bf16 v[56:59], v[140:143], v[182:185], v[56:59]
	v_mfma_f32_16x16x32_bf16 v[108:111], v[132:135], v[232:235], v[108:111]
	v_mfma_f32_16x16x32_bf16 v[44:47], v[140:143], v[232:235], v[44:47]
	v_mfma_f32_16x16x32_bf16 v[100:103], v[132:135], v[240:243], v[100:103]
	v_mfma_f32_16x16x32_bf16 v[36:39], v[140:143], v[240:243], v[36:39]
	s_setprio 0
	s_setprio 1
	v_mfma_f32_16x16x32_bf16 v[116:119], v[144:147], v[160:163], v[116:119]
	v_mfma_f32_16x16x32_bf16 v[52:55], v[152:155], v[160:163], v[52:55]
	v_mfma_f32_16x16x32_bf16 v[112:115], v[144:147], v[178:181], v[112:115]
	v_mfma_f32_16x16x32_bf16 v[48:51], v[152:155], v[178:181], v[48:51]
	v_mfma_f32_16x16x32_bf16 v[104:107], v[144:147], v[192:195], v[104:107]
	v_mfma_f32_16x16x32_bf16 v[40:43], v[152:155], v[192:195], v[40:43]
	v_mfma_f32_16x16x32_bf16 v[96:99], v[144:147], v[236:239], v[96:99]
	v_mfma_f32_16x16x32_bf16 v[32:35], v[152:155], v[236:239], v[32:35]
	v_mfma_f32_16x16x32_bf16 v[116:119], v[148:151], v[164:167], v[116:119]
	v_mfma_f32_16x16x32_bf16 v[52:55], v[156:159], v[164:167], v[52:55]
	v_mfma_f32_16x16x32_bf16 v[112:115], v[148:151], v[182:185], v[112:115]
	v_mfma_f32_16x16x32_bf16 v[48:51], v[156:159], v[182:185], v[48:51]
	v_mfma_f32_16x16x32_bf16 v[104:107], v[148:151], v[232:235], v[104:107]
	v_mfma_f32_16x16x32_bf16 v[40:43], v[156:159], v[232:235], v[40:43]
	v_mfma_f32_16x16x32_bf16 v[96:99], v[148:151], v[240:243], v[96:99]
	v_mfma_f32_16x16x32_bf16 v[32:35], v[156:159], v[240:243], v[32:35]
	s_setprio 0
	s_barrier
	s_add_i32 s71, s71, s53
	v_lshl_add_u64 v[186:187], s[10:11], 0, v[188:189]
	s_mov_b32 m0, s71
	ds_read_b128 v[160:163], v230 offset:16384
	ds_read_b128 v[164:167], v230 offset:17408
	ds_read_b128 v[178:181], v230 offset:18432
	ds_read_b128 v[182:185], v230 offset:19456
	ds_read_b128 v[192:195], v230 offset:20480
	ds_read_b128 v[232:235], v230 offset:21504
	ds_read_b128 v[236:239], v230 offset:22528
	ds_read_b128 v[240:243], v230 offset:23552
	global_load_lds_dwordx4 v[186:187], off
	s_add_i32 m0, s71, 0x2000
	s_add_u32 s72, s10, 0x40000
	v_lshl_add_u64 v[244:245], s[10:11], 0, v[172:173]
	s_addc_u32 s73, s11, 0
	s_add_i32 s71, s74, s53
	global_load_lds_dwordx4 v[244:245], off
	v_lshl_add_u64 v[246:247], s[72:73], 0, v[188:189]
	s_mov_b32 m0, s71
	v_lshl_add_u64 v[248:249], s[44:45], 0, v[170:171]
	global_load_lds_dwordx4 v[246:247], off
	s_add_i32 m0, s71, 0x2000
	v_lshl_add_u64 v[246:247], s[72:73], 0, v[172:173]
	global_load_lds_dwordx4 v[246:247], off
	s_mov_b32 m0, s54
	v_lshl_add_u64 v[246:247], s[44:45], 0, v[168:169]
	global_load_lds_dwordx4 v[246:247], off
	s_mov_b32 m0, s55
	s_nop 0
	global_load_lds_dwordx4 v[248:249], off
	s_waitcnt vmcnt(8)
	s_waitcnt lgkmcnt(0)
	s_barrier
; #define PG8_STAGE(bufoff, gbase, voff) do { _Pragma("unroll") for (int _i = 0; _i < 2; ++_i) \
;         __builtin_amdgcn_global_load_lds((const unsigned*)((const char*)(gbase) + (voff)[_i]), (PG8_LAS unsigned*)(lds + (bufoff) + ldsw + _i * 8192), 16, 0, 0); } while (0)
; #define PG8_LDA(dst, b, h) do { _Pragma("unroll") for (int m = 0; m < 4; ++m) _Pragma("unroll") for (int k = 0; k < 2; ++k) dst[m][k] = *(const PG8_LAS bf16x8*)(lds + PG8_SA(b, h) + aoff + m * 2048 + k * 1024); } while (0)
; #define PG8_LDB(dst, b, h) do { _Pragma("unroll") for (int n = 0; n < 2; ++n) _Pragma("unroll") for (int k = 0; k < 2; ++k) dst[n][k] = *(const PG8_LAS bf16x8*)(lds + PG8_SB(b, h) + boff + n * 2048 + k * 1024); } while (0)
; #define PG8_MMA(ai, bj, At, Bt) do { __builtin_amdgcn_s_setprio(1); _Pragma("unroll") for (int m = 0; m < 4; ++m) _Pragma("unroll") for (int n = 0; n < 2; ++n) _Pragma("unroll") for (int k = 0; k < 2; ++k) \
;         acc[ai][bj][m][n] = __builtin_amdgcn_mfma_f32_16x16x32_bf16(Bt[n][k], At[m][k], acc[ai][bj][m][n], 0, 0, 0); __builtin_amdgcn_s_setprio(0); } while (0)
; #define PG8_WAIT_V(n) asm volatile("s_waitcnt vmcnt(" #n ")" ::: "memory")
; #define PG8_WAIT_L(n) asm volatile("s_waitcnt lgkmcnt(" #n ")" ::: "memory")
; #define PG8_BAR __builtin_amdgcn_s_barrier()
; #define PG8_SCHED __builtin_amdgcn_sched_barrier(0)
; template <class Epi, class Sched, bool ALIGN_EPI = false, bool SP2 = false>
; __device__ __forceinline__ void gemm_phase(PG8_LAS unsigned char* lds, const Gemm g, const Sched& S, const Epi& E) {
;     ...
;             PG8_WAIT_V(8); PG8_WAIT_L(0); PG8_BAR; PG8_MMA(1, 0, At, B0); PG8_MMA(1, 1, At, B1); PG8_BAR; PG8_SCHED;
;             PG8_LDB(B0, 1, 0); PG8_LDB(B1, 1, 1); PG8_SCHED; PG8_LDA(At, 1, 0); PG8_STAGE(PG8_SA(0, 1), a2 + hstepA, voffA);
;             PG8_WAIT_V(8); PG8_WAIT_L(0); PG8_BAR; PG8_MMA(0, 0, At, B0); PG8_MMA(0, 1, At, B1); PG8_BAR; PG8_SCHED;
	s_setprio 1
	s_waitcnt lgkmcnt(0)
	v_mfma_f32_16x16x32_bf16 v[92:95], v[128:131], v[160:163], v[92:95]
	v_mfma_f32_16x16x32_bf16 v[28:31], v[136:139], v[160:163], v[28:31]
	v_mfma_f32_16x16x32_bf16 v[88:91], v[128:131], v[178:181], v[88:91]
	v_mfma_f32_16x16x32_bf16 v[24:27], v[136:139], v[178:181], v[24:27]
	v_mfma_f32_16x16x32_bf16 v[76:79], v[128:131], v[192:195], v[76:79]
	v_mfma_f32_16x16x32_bf16 v[12:15], v[136:139], v[192:195], v[12:15]
	v_mfma_f32_16x16x32_bf16 v[68:71], v[128:131], v[236:239], v[68:71]
	v_mfma_f32_16x16x32_bf16 v[4:7], v[136:139], v[236:239], v[4:7]
	v_mfma_f32_16x16x32_bf16 v[92:95], v[132:135], v[164:167], v[92:95]
	v_mfma_f32_16x16x32_bf16 v[28:31], v[140:143], v[164:167], v[28:31]
	v_mfma_f32_16x16x32_bf16 v[88:91], v[132:135], v[182:185], v[88:91]
	v_mfma_f32_16x16x32_bf16 v[24:27], v[140:143], v[182:185], v[24:27]
	v_mfma_f32_16x16x32_bf16 v[76:79], v[132:135], v[232:235], v[76:79]
	v_mfma_f32_16x16x32_bf16 v[12:15], v[140:143], v[232:235], v[12:15]
	v_mfma_f32_16x16x32_bf16 v[68:71], v[132:135], v[240:243], v[68:71]
	v_mfma_f32_16x16x32_bf16 v[4:7], v[140:143], v[240:243], v[4:7]
	s_setprio 0
	s_setprio 1
	v_mfma_f32_16x16x32_bf16 v[84:87], v[144:147], v[160:163], v[84:87]
	v_mfma_f32_16x16x32_bf16 v[20:23], v[152:155], v[160:163], v[20:23]
	v_mfma_f32_16x16x32_bf16 v[80:83], v[144:147], v[178:181], v[80:83]
	v_mfma_f32_16x16x32_bf16 v[16:19], v[152:155], v[178:181], v[16:19]
	v_mfma_f32_16x16x32_bf16 v[72:75], v[144:147], v[192:195], v[72:75]
	v_mfma_f32_16x16x32_bf16 v[8:11], v[152:155], v[192:195], v[8:11]
	v_mfma_f32_16x16x32_bf16 v[64:67], v[144:147], v[236:239], v[64:67]
	v_mfma_f32_16x16x32_bf16 v[0:3], v[152:155], v[236:239], v[0:3]
	v_mfma_f32_16x16x32_bf16 v[84:87], v[148:151], v[164:167], v[84:87]
	v_mfma_f32_16x16x32_bf16 v[20:23], v[156:159], v[164:167], v[20:23]
	v_mfma_f32_16x16x32_bf16 v[80:83], v[148:151], v[182:185], v[80:83]
	v_mfma_f32_16x16x32_bf16 v[16:19], v[156:159], v[182:185], v[16:19]
	v_mfma_f32_16x16x32_bf16 v[72:75], v[148:151], v[232:235], v[72:75]
	v_mfma_f32_16x16x32_bf16 v[8:11], v[156:159], v[232:235], v[8:11]
	v_mfma_f32_16x16x32_bf16 v[64:67], v[148:151], v[240:243], v[64:67]
	v_mfma_f32_16x16x32_bf16 v[0:3], v[156:159], v[240:243], v[0:3]
	s_setprio 0
	s_barrier
	s_add_i32 s71, 0, 0x18000
	s_add_i32 s72, 0, 0x1c000
	v_add_u32_e32 v140, s71, v229
	v_add_u32_e32 v156, s72, v229
	ds_read_b128 v[128:131], v140
	ds_read_b128 v[132:135], v140 offset:1024
	ds_read_b128 v[136:139], v140 offset:2048
	ds_read_b128 v[140:143], v140 offset:3072
	ds_read_b128 v[144:147], v156
	ds_read_b128 v[148:151], v156 offset:1024
	ds_read_b128 v[152:155], v156 offset:2048
	ds_read_b128 v[156:159], v156 offset:3072
	s_add_u32 s44, s44, 0x40000
	s_addc_u32 s45, s45, 0
	s_mov_b32 m0, s56
	v_lshl_add_u64 v[250:251], s[44:45], 0, v[168:169]
	ds_read_b128 v[160:163], v230 offset:32768
	ds_read_b128 v[164:167], v230 offset:33792
	ds_read_b128 v[178:181], v230 offset:34816
	ds_read_b128 v[182:185], v230 offset:35840
	ds_read_b128 v[192:195], v230 offset:36864
	ds_read_b128 v[232:235], v230 offset:37888
	ds_read_b128 v[236:239], v230 offset:38912
	ds_read_b128 v[240:243], v230 offset:39936
	global_load_lds_dwordx4 v[250:251], off
	s_mov_b32 m0, s57
	v_lshl_add_u64 v[250:251], s[44:45], 0, v[170:171]
	global_load_lds_dwordx4 v[250:251], off
	s_waitcnt vmcnt(8)
	s_waitcnt lgkmcnt(0)
	s_barrier
	s_setprio 1
	s_waitcnt lgkmcnt(0)
	v_mfma_f32_16x16x32_bf16 v[124:127], v[128:131], v[160:163], v[124:127]
	v_mfma_f32_16x16x32_bf16 v[60:63], v[136:139], v[160:163], v[60:63]
	v_mfma_f32_16x16x32_bf16 v[120:123], v[128:131], v[178:181], v[120:123]
	v_mfma_f32_16x16x32_bf16 v[56:59], v[136:139], v[178:181], v[56:59]
	v_mfma_f32_16x16x32_bf16 v[108:111], v[128:131], v[192:195], v[108:111]
	v_mfma_f32_16x16x32_bf16 v[44:47], v[136:139], v[192:195], v[44:47]
	v_mfma_f32_16x16x32_bf16 v[100:103], v[128:131], v[236:239], v[100:103]
	v_mfma_f32_16x16x32_bf16 v[36:39], v[136:139], v[236:239], v[36:39]
	v_mfma_f32_16x16x32_bf16 v[124:127], v[132:135], v[164:167], v[124:127]
	v_mfma_f32_16x16x32_bf16 v[60:63], v[140:143], v[164:167], v[60:63]
	v_mfma_f32_16x16x32_bf16 v[120:123], v[132:135], v[182:185], v[120:123]
	v_mfma_f32_16x16x32_bf16 v[56:59], v[140:143], v[182:185], v[56:59]
	v_mfma_f32_16x16x32_bf16 v[108:111], v[132:135], v[232:235], v[108:111]
	v_mfma_f32_16x16x32_bf16 v[44:47], v[140:143], v[232:235], v[44:47]
	v_mfma_f32_16x16x32_bf16 v[100:103], v[132:135], v[240:243], v[100:103]
	v_mfma_f32_16x16x32_bf16 v[36:39], v[140:143], v[240:243], v[36:39]
	s_setprio 0
	s_setprio 1
	v_mfma_f32_16x16x32_bf16 v[116:119], v[144:147], v[160:163], v[116:119]
	v_mfma_f32_16x16x32_bf16 v[52:55], v[152:155], v[160:163], v[52:55]
	v_mfma_f32_16x16x32_bf16 v[112:115], v[144:147], v[178:181], v[112:115]
	v_mfma_f32_16x16x32_bf16 v[48:51], v[152:155], v[178:181], v[48:51]
	v_mfma_f32_16x16x32_bf16 v[104:107], v[144:147], v[192:195], v[104:107]
	v_mfma_f32_16x16x32_bf16 v[40:43], v[152:155], v[192:195], v[40:43]
	v_mfma_f32_16x16x32_bf16 v[96:99], v[144:147], v[236:239], v[96:99]
	v_mfma_f32_16x16x32_bf16 v[32:35], v[152:155], v[236:239], v[32:35]
	v_mfma_f32_16x16x32_bf16 v[116:119], v[148:151], v[164:167], v[116:119]
	v_mfma_f32_16x16x32_bf16 v[52:55], v[156:159], v[164:167], v[52:55]
	v_mfma_f32_16x16x32_bf16 v[112:115], v[148:151], v[182:185], v[112:115]
	v_mfma_f32_16x16x32_bf16 v[48:51], v[156:159], v[182:185], v[48:51]
	v_mfma_f32_16x16x32_bf16 v[104:107], v[148:151], v[232:235], v[104:107]
	v_mfma_f32_16x16x32_bf16 v[40:43], v[156:159], v[232:235], v[40:43]
	v_mfma_f32_16x16x32_bf16 v[96:99], v[148:151], v[240:243], v[96:99]
	v_mfma_f32_16x16x32_bf16 v[32:35], v[156:159], v[240:243], v[32:35]
	s_setprio 0
	s_barrier
; #define PG8_STAGE(bufoff, gbase, voff) do { _Pragma("unroll") for (int _i = 0; _i < 2; ++_i) \
;         __builtin_amdgcn_global_load_lds((const unsigned*)((const char*)(gbase) + (voff)[_i]), (PG8_LAS unsigned*)(lds + (bufoff) + ldsw + _i * 8192), 16, 0, 0); } while (0)
; #define PG8_LDA(dst, b, h) do { _Pragma("unroll") for (int m = 0; m < 4; ++m) _Pragma("unroll") for (int k = 0; k < 2; ++k) dst[m][k] = *(const PG8_LAS bf16x8*)(lds + PG8_SA(b, h) + aoff + m * 2048 + k * 1024); } while (0)
; #define PG8_MMA(ai, bj, At, Bt) do { __builtin_amdgcn_s_setprio(1); _Pragma("unroll") for (int m = 0; m < 4; ++m) _Pragma("unroll") for (int n = 0; n < 2; ++n) _Pragma("unroll") for (int k = 0; k < 2; ++k) \
;         acc[ai][bj][m][n] = __builtin_amdgcn_mfma_f32_16x16x32_bf16(Bt[n][k], At[m][k], acc[ai][bj][m][n], 0, 0, 0); __builtin_amdgcn_s_setprio(0); } while (0)
; #define PG8_WAIT_V(n) asm volatile("s_waitcnt vmcnt(" #n ")" ::: "memory")
; #define PG8_WAIT_L(n) asm volatile("s_waitcnt lgkmcnt(" #n ")" ::: "memory")
; #define PG8_BAR __builtin_amdgcn_s_barrier()
; #define PG8_SCHED __builtin_amdgcn_sched_barrier(0)
; template <class Epi, class Sched, bool ALIGN_EPI = false, bool SP2 = false>
; __device__ __forceinline__ void gemm_phase(PG8_LAS unsigned char* lds, const Gemm g, const Sched& S, const Epi& E) {
;     ...
;             PG8_LDA(At, 1, 1); PG8_STAGE(PG8_SB(1, 0), b3, voffB); PG8_STAGE(PG8_SB(1, 1), b3 + hstepB, voffB); PG8_STAGE(PG8_SA(1, 0), a3, voffA);
;             PG8_WAIT_V(8); PG8_WAIT_L(0); PG8_BAR; PG8_MMA(1, 0, At, B0); PG8_MMA(1, 1, At, B1); PG8_BAR; PG8_SCHED;
	s_add_i32 s44, s71, s53
	v_lshl_add_u64 v[186:187], v[186:187], 0, s[94:95]
	s_mov_b32 m0, s44
	ds_read_b128 v[160:163], v230 offset:49152
	ds_read_b128 v[164:167], v230 offset:50176
	ds_read_b128 v[178:181], v230 offset:51200
	ds_read_b128 v[182:185], v230 offset:52224
	ds_read_b128 v[192:195], v230 offset:53248
	ds_read_b128 v[232:235], v230 offset:54272
	ds_read_b128 v[236:239], v230 offset:55296
	ds_read_b128 v[240:243], v230 offset:56320
	global_load_lds_dwordx4 v[186:187], off
	s_add_i32 m0, s44, 0x2000
	s_add_u32 s10, s10, 0x40080
	v_lshl_add_u64 v[186:187], v[244:245], 0, s[94:95]
	s_addc_u32 s11, s11, 0
	s_add_i32 s44, s72, s53
	global_load_lds_dwordx4 v[186:187], off
	s_mov_b32 m0, s44
	v_lshl_add_u64 v[186:187], s[10:11], 0, v[188:189]
	global_load_lds_dwordx4 v[186:187], off
	s_add_i32 m0, s44, 0x2000
	v_lshl_add_u64 v[186:187], s[10:11], 0, v[172:173]
	global_load_lds_dwordx4 v[186:187], off
	s_mov_b32 m0, s60
	v_lshl_add_u64 v[186:187], v[246:247], 0, s[94:95]
	global_load_lds_dwordx4 v[186:187], off
	s_mov_b32 m0, s61
	v_lshl_add_u64 v[186:187], v[248:249], 0, s[94:95]
	global_load_lds_dwordx4 v[186:187], off
	s_waitcnt vmcnt(8)
	s_waitcnt lgkmcnt(0)
	s_barrier
	s_setprio 1
	s_waitcnt lgkmcnt(0)
	v_mfma_f32_16x16x32_bf16 v[92:95], v[128:131], v[160:163], v[92:95]
	v_mfma_f32_16x16x32_bf16 v[28:31], v[136:139], v[160:163], v[28:31]
	v_mfma_f32_16x16x32_bf16 v[88:91], v[128:131], v[178:181], v[88:91]
	v_mfma_f32_16x16x32_bf16 v[24:27], v[136:139], v[178:181], v[24:27]
	v_mfma_f32_16x16x32_bf16 v[76:79], v[128:131], v[192:195], v[76:79]
	v_mfma_f32_16x16x32_bf16 v[12:15], v[136:139], v[192:195], v[12:15]
	v_mfma_f32_16x16x32_bf16 v[68:71], v[128:131], v[236:239], v[68:71]
	v_mfma_f32_16x16x32_bf16 v[4:7], v[136:139], v[236:239], v[4:7]
	v_mfma_f32_16x16x32_bf16 v[92:95], v[132:135], v[164:167], v[92:95]
	v_mfma_f32_16x16x32_bf16 v[28:31], v[140:143], v[164:167], v[28:31]
	v_mfma_f32_16x16x32_bf16 v[88:91], v[132:135], v[182:185], v[88:91]
	v_mfma_f32_16x16x32_bf16 v[24:27], v[140:143], v[182:185], v[24:27]
	v_mfma_f32_16x16x32_bf16 v[76:79], v[132:135], v[232:235], v[76:79]
	v_mfma_f32_16x16x32_bf16 v[12:15], v[140:143], v[232:235], v[12:15]
	v_mfma_f32_16x16x32_bf16 v[68:71], v[132:135], v[240:243], v[68:71]
	v_mfma_f32_16x16x32_bf16 v[4:7], v[140:143], v[240:243], v[4:7]
	s_setprio 0
	s_setprio 1
	v_mfma_f32_16x16x32_bf16 v[84:87], v[144:147], v[160:163], v[84:87]
	v_mfma_f32_16x16x32_bf16 v[20:23], v[152:155], v[160:163], v[20:23]
	v_mfma_f32_16x16x32_bf16 v[80:83], v[144:147], v[178:181], v[80:83]
	v_mfma_f32_16x16x32_bf16 v[16:19], v[152:155], v[178:181], v[16:19]
	v_mfma_f32_16x16x32_bf16 v[72:75], v[144:147], v[192:195], v[72:75]
	v_mfma_f32_16x16x32_bf16 v[8:11], v[152:155], v[192:195], v[8:11]
	v_mfma_f32_16x16x32_bf16 v[64:67], v[144:147], v[236:239], v[64:67]
	v_mfma_f32_16x16x32_bf16 v[0:3], v[152:155], v[236:239], v[0:3]
	v_mfma_f32_16x16x32_bf16 v[84:87], v[148:151], v[164:167], v[84:87]
	v_mfma_f32_16x16x32_bf16 v[20:23], v[156:159], v[164:167], v[20:23]
	v_mfma_f32_16x16x32_bf16 v[80:83], v[148:151], v[182:185], v[80:83]
	v_mfma_f32_16x16x32_bf16 v[16:19], v[156:159], v[182:185], v[16:19]
	v_mfma_f32_16x16x32_bf16 v[72:75], v[148:151], v[232:235], v[72:75]
	v_mfma_f32_16x16x32_bf16 v[8:11], v[156:159], v[232:235], v[8:11]
	v_mfma_f32_16x16x32_bf16 v[64:67], v[148:151], v[240:243], v[64:67]
	v_mfma_f32_16x16x32_bf16 v[0:3], v[156:159], v[240:243], v[0:3]
	s_setprio 0
	s_barrier
	s_add_i32 s70, s70, 2
	s_add_u32 s8, s8, 0x100
	s_addc_u32 s9, s9, 0
	s_add_u32 s46, s46, 0x100
	s_addc_u32 s47, s47, 0
	s_cmp_gt_u32 s70, 13
	s_cbranch_scc0 .LBB0_1800
	s_and_b64 vcc, exec, s[26:27]
	s_cbranch_vccz .LBB0_1803
	s_barrier

; #define PG8_STAGE(bufoff, gbase, voff) do { _Pragma("unroll") for (int _i = 0; _i < 2; ++_i) \
;         __builtin_amdgcn_global_load_lds((const unsigned*)((const char*)(gbase) + (voff)[_i]), (PG8_LAS unsigned*)(lds + (bufoff) + ldsw + _i * 8192), 16, 0, 0); } while (0)
; #define PG8_LDA(dst, b, h) do { _Pragma("unroll") for (int m = 0; m < 4; ++m) _Pragma("unroll") for (int k = 0; k < 2; ++k) dst[m][k] = *(const PG8_LAS bf16x8*)(lds + PG8_SA(b, h) + aoff + m * 2048 + k * 1024); } while (0)
; #define PG8_LDB(dst, b, h) do { _Pragma("unroll") for (int n = 0; n < 2; ++n) _Pragma("unroll") for (int k = 0; k < 2; ++k) dst[n][k] = *(const PG8_LAS bf16x8*)(lds + PG8_SB(b, h) + boff + n * 2048 + k * 1024); } while (0)
; #define PG8_MMA(ai, bj, At, Bt) do { __builtin_amdgcn_s_setprio(1); _Pragma("unroll") for (int m = 0; m < 4; ++m) _Pragma("unroll") for (int n = 0; n < 2; ++n) _Pragma("unroll") for (int k = 0; k < 2; ++k) \
;         acc[ai][bj][m][n] = __builtin_amdgcn_mfma_f32_16x16x32_bf16(Bt[n][k], At[m][k], acc[ai][bj][m][n], 0, 0, 0); __builtin_amdgcn_s_setprio(0); } while (0)
; #define PG8_WAIT_V(n) asm volatile("s_waitcnt vmcnt(" #n ")" ::: "memory")
; #define PG8_WAIT_L(n) asm volatile("s_waitcnt lgkmcnt(" #n ")" ::: "memory")
; #define PG8_BAR __builtin_amdgcn_s_barrier()
; #define PG8_SCHED __builtin_amdgcn_sched_barrier(0)
; template <class Epi, class Sched, bool ALIGN_EPI = false, bool SP2 = false>
; __device__ __forceinline__ void gemm_phase(PG8_LAS unsigned char* lds, const Gemm g, const Sched& S, const Epi& E) {
;     ...
;             const bool last = (t == nt - 2);
;             const char* a1 = cA + (size_t)(t + 1) * kstep;
;             const char* a2 = last ? nA : cA + (size_t)(t + 2) * kstep; const char* b2 = last ? nB : cB + (size_t)(t + 2) * kstep;
;             const char* a3 = a2 + kstep; const char* b3 = b2 + kstep;
;             if (last && has_next) S.a_ready(nxt);
;             if constexpr (SP2) {
;             PG8_LDB(B0, 0, 0); PG8_LDB(B1, 0, 1); PG8_SCHED; PG8_LDA(At, 0, 0); PG8_STAGE(PG8_SA(1, 1), a1 + hstepA, voffA);
;             PG8_WAIT_V(8); PG8_WAIT_L(0); PG8_BAR; PG8_MMA(0, 0, At, B0); PG8_MMA(0, 1, At, B1); PG8_BAR; PG8_SCHED;
;             PG8_LDA(At, 0, 1); PG8_STAGE(PG8_SB(0, 0), b2, voffB); PG8_STAGE(PG8_SB(0, 1), b2 + hstepB, voffB); PG8_STAGE(PG8_SA(0, 0), a2, voffA);
.LBB0_1993:
	s_add_u32 s24, s22, 0x100
	s_addc_u32 s25, s23, 0
	s_add_i32 s68, 0, 0x10000
	s_cmp_eq_u32 s67, 40
	s_cselect_b32 s29, s9, s25
	s_cselect_b32 s28, s8, s24
	s_cselect_b32 s27, s21, s66
	s_cselect_b32 s26, s20, s65
	s_add_i32 s69, 0, 0x14000
	v_add_u32_e32 v150, s68, v140
	v_add_u32_e32 v166, s69, v140
	ds_read_b128 v[134:137], v150
	ds_read_b128 v[142:145], v150 offset:1024
	ds_read_b128 v[146:149], v150 offset:2048
	ds_read_b128 v[150:153], v150 offset:3072
	ds_read_b128 v[154:157], v166
	ds_read_b128 v[158:161], v166 offset:1024
	ds_read_b128 v[162:165], v166 offset:2048
	ds_read_b128 v[166:169], v166 offset:3072
	v_lshl_add_u64 v[186:187], s[22:23], 0, v[130:131]
	s_add_i32 m0, s36, 0xc000
	ds_read_b128 v[170:173], v141
	ds_read_b128 v[174:177], v141 offset:1024
	ds_read_b128 v[178:181], v141 offset:2048
	ds_read_b128 v[182:185], v141 offset:3072
	ds_read_b128 v[192:195], v141 offset:4096
	ds_read_b128 v[230:233], v141 offset:5120
	ds_read_b128 v[234:237], v141 offset:6144
	ds_read_b128 v[238:241], v141 offset:7168
	global_load_lds_dwordx4 v[186:187], off
	s_add_i32 m0, s36, 0xe000
	v_lshl_add_u64 v[186:187], s[22:23], 0, v[132:133]
	global_load_lds_dwordx4 v[186:187], off
	s_waitcnt vmcnt(8)
	s_waitcnt lgkmcnt(0)
	s_barrier
	s_setprio 1
	s_waitcnt lgkmcnt(0)
	v_mfma_f32_16x16x32_bf16 v[124:127], v[134:137], v[170:173], v[124:127]
	v_mfma_f32_16x16x32_bf16 v[96:99], v[146:149], v[170:173], v[96:99]
	v_mfma_f32_16x16x32_bf16 v[120:123], v[134:137], v[178:181], v[120:123]
	v_mfma_f32_16x16x32_bf16 v[92:95], v[146:149], v[178:181], v[92:95]
	v_mfma_f32_16x16x32_bf16 v[116:119], v[134:137], v[192:195], v[116:119]
	v_mfma_f32_16x16x32_bf16 v[84:87], v[146:149], v[192:195], v[84:87]
	v_mfma_f32_16x16x32_bf16 v[112:115], v[134:137], v[234:237], v[112:115]
	v_mfma_f32_16x16x32_bf16 v[80:83], v[146:149], v[234:237], v[80:83]
	v_mfma_f32_16x16x32_bf16 v[124:127], v[142:145], v[174:177], v[124:127]
	v_mfma_f32_16x16x32_bf16 v[96:99], v[150:153], v[174:177], v[96:99]
	v_mfma_f32_16x16x32_bf16 v[120:123], v[142:145], v[182:185], v[120:123]
	v_mfma_f32_16x16x32_bf16 v[92:95], v[150:153], v[182:185], v[92:95]
	v_mfma_f32_16x16x32_bf16 v[116:119], v[142:145], v[230:233], v[116:119]
	v_mfma_f32_16x16x32_bf16 v[84:87], v[150:153], v[230:233], v[84:87]
	v_mfma_f32_16x16x32_bf16 v[112:115], v[142:145], v[238:241], v[112:115]
	v_mfma_f32_16x16x32_bf16 v[80:83], v[150:153], v[238:241], v[80:83]
	s_setprio 0
	s_setprio 1
	v_mfma_f32_16x16x32_bf16 v[64:67], v[154:157], v[170:173], v[64:67]
	v_mfma_f32_16x16x32_bf16 v[36:39], v[162:165], v[170:173], v[36:39]
	v_mfma_f32_16x16x32_bf16 v[56:59], v[154:157], v[178:181], v[56:59]
	v_mfma_f32_16x16x32_bf16 v[24:27], v[162:165], v[178:181], v[24:27]
	v_mfma_f32_16x16x32_bf16 v[52:55], v[154:157], v[192:195], v[52:55]
	v_mfma_f32_16x16x32_bf16 v[20:23], v[162:165], v[192:195], v[20:23]
	v_mfma_f32_16x16x32_bf16 v[48:51], v[154:157], v[234:237], v[48:51]
	v_mfma_f32_16x16x32_bf16 v[16:19], v[162:165], v[234:237], v[16:19]
	v_mfma_f32_16x16x32_bf16 v[64:67], v[158:161], v[174:177], v[64:67]
	v_mfma_f32_16x16x32_bf16 v[36:39], v[166:169], v[174:177], v[36:39]
	v_mfma_f32_16x16x32_bf16 v[56:59], v[158:161], v[182:185], v[56:59]
	v_mfma_f32_16x16x32_bf16 v[24:27], v[166:169], v[182:185], v[24:27]
	v_mfma_f32_16x16x32_bf16 v[52:55], v[158:161], v[230:233], v[52:55]
	v_mfma_f32_16x16x32_bf16 v[20:23], v[166:169], v[230:233], v[20:23]
	v_mfma_f32_16x16x32_bf16 v[48:51], v[158:161], v[238:241], v[48:51]
	v_mfma_f32_16x16x32_bf16 v[16:19], v[166:169], v[238:241], v[16:19]
	s_setprio 0
	s_barrier
	s_add_i32 s22, s68, s35
	v_lshl_add_u64 v[186:187], s[26:27], 0, v[188:189]
	s_mov_b32 m0, s22
	ds_read_b128 v[170:173], v141 offset:16384
	ds_read_b128 v[174:177], v141 offset:17408
	ds_read_b128 v[178:181], v141 offset:18432
	ds_read_b128 v[182:185], v141 offset:19456
	ds_read_b128 v[192:195], v141 offset:20480
	ds_read_b128 v[230:233], v141 offset:21504
	ds_read_b128 v[234:237], v141 offset:22528
	ds_read_b128 v[238:241], v141 offset:23552
	global_load_lds_dwordx4 v[186:187], off
	s_add_i32 m0, s22, 0x2000
	s_add_u32 s22, s26, 0xb0000
	v_lshl_add_u64 v[196:197], s[26:27], 0, v[128:129]
	s_addc_u32 s23, s27, 0
	s_add_i32 s68, s69, s35
	global_load_lds_dwordx4 v[196:197], off
	v_lshl_add_u64 v[242:243], s[22:23], 0, v[188:189]
	s_mov_b32 m0, s68
	v_lshl_add_u64 v[244:245], s[28:29], 0, v[128:129]
	global_load_lds_dwordx4 v[242:243], off
	s_add_i32 m0, s68, 0x2000
	v_lshl_add_u64 v[242:243], s[22:23], 0, v[128:129]
	global_load_lds_dwordx4 v[242:243], off
	s_mov_b32 m0, s36
	v_lshl_add_u64 v[242:243], s[28:29], 0, v[188:189]
	global_load_lds_dwordx4 v[242:243], off
	s_mov_b32 m0, s37
	s_nop 0
	global_load_lds_dwordx4 v[244:245], off
	s_waitcnt vmcnt(8)
	s_waitcnt lgkmcnt(0)
	s_barrier
; #define PG8_STAGE(bufoff, gbase, voff) do { _Pragma("unroll") for (int _i = 0; _i < 2; ++_i) \
;         __builtin_amdgcn_global_load_lds((const unsigned*)((const char*)(gbase) + (voff)[_i]), (PG8_LAS unsigned*)(lds + (bufoff) + ldsw + _i * 8192), 16, 0, 0); } while (0)
; #define PG8_LDA(dst, b, h) do { _Pragma("unroll") for (int m = 0; m < 4; ++m) _Pragma("unroll") for (int k = 0; k < 2; ++k) dst[m][k] = *(const PG8_LAS bf16x8*)(lds + PG8_SA(b, h) + aoff + m * 2048 + k * 1024); } while (0)
; #define PG8_LDB(dst, b, h) do { _Pragma("unroll") for (int n = 0; n < 2; ++n) _Pragma("unroll") for (int k = 0; k < 2; ++k) dst[n][k] = *(const PG8_LAS bf16x8*)(lds + PG8_SB(b, h) + boff + n * 2048 + k * 1024); } while (0)
; #define PG8_MMA(ai, bj, At, Bt) do { __builtin_amdgcn_s_setprio(1); _Pragma("unroll") for (int m = 0; m < 4; ++m) _Pragma("unroll") for (int n = 0; n < 2; ++n) _Pragma("unroll") for (int k = 0; k < 2; ++k) \
;         acc[ai][bj][m][n] = __builtin_amdgcn_mfma_f32_16x16x32_bf16(Bt[n][k], At[m][k], acc[ai][bj][m][n], 0, 0, 0); __builtin_amdgcn_s_setprio(0); } while (0)
; #define PG8_WAIT_V(n) asm volatile("s_waitcnt vmcnt(" #n ")" ::: "memory")
; #define PG8_WAIT_L(n) asm volatile("s_waitcnt lgkmcnt(" #n ")" ::: "memory")
; #define PG8_BAR __builtin_amdgcn_s_barrier()
; #define PG8_SCHED __builtin_amdgcn_sched_barrier(0)
; template <class Epi, class Sched, bool ALIGN_EPI = false, bool SP2 = false>
; __device__ __forceinline__ void gemm_phase(PG8_LAS unsigned char* lds, const Gemm g, const Sched& S, const Epi& E) {
;     ...
;             PG8_WAIT_V(8); PG8_WAIT_L(0); PG8_BAR; PG8_MMA(1, 0, At, B0); PG8_MMA(1, 1, At, B1); PG8_BAR; PG8_SCHED;
;             PG8_LDB(B0, 1, 0); PG8_LDB(B1, 1, 1); PG8_SCHED; PG8_LDA(At, 1, 0); PG8_STAGE(PG8_SA(0, 1), a2 + hstepA, voffA);
;             PG8_WAIT_V(8); PG8_WAIT_L(0); PG8_BAR; PG8_MMA(0, 0, At, B0); PG8_MMA(0, 1, At, B1); PG8_BAR; PG8_SCHED;
	s_setprio 1
	s_waitcnt lgkmcnt(0)
	v_mfma_f32_16x16x32_bf16 v[108:111], v[134:137], v[170:173], v[108:111]
	v_mfma_f32_16x16x32_bf16 v[76:79], v[146:149], v[170:173], v[76:79]
	v_mfma_f32_16x16x32_bf16 v[104:107], v[134:137], v[178:181], v[104:107]
	v_mfma_f32_16x16x32_bf16 v[72:75], v[146:149], v[178:181], v[72:75]
	v_mfma_f32_16x16x32_bf16 v[100:103], v[134:137], v[192:195], v[100:103]
	v_mfma_f32_16x16x32_bf16 v[68:71], v[146:149], v[192:195], v[68:71]
	v_mfma_f32_16x16x32_bf16 v[88:91], v[134:137], v[234:237], v[88:91]
	v_mfma_f32_16x16x32_bf16 v[60:63], v[146:149], v[234:237], v[60:63]
	v_mfma_f32_16x16x32_bf16 v[108:111], v[142:145], v[174:177], v[108:111]
	v_mfma_f32_16x16x32_bf16 v[76:79], v[150:153], v[174:177], v[76:79]
	v_mfma_f32_16x16x32_bf16 v[104:107], v[142:145], v[182:185], v[104:107]
	v_mfma_f32_16x16x32_bf16 v[72:75], v[150:153], v[182:185], v[72:75]
	v_mfma_f32_16x16x32_bf16 v[100:103], v[142:145], v[230:233], v[100:103]
	v_mfma_f32_16x16x32_bf16 v[68:71], v[150:153], v[230:233], v[68:71]
	v_mfma_f32_16x16x32_bf16 v[88:91], v[142:145], v[238:241], v[88:91]
	v_mfma_f32_16x16x32_bf16 v[60:63], v[150:153], v[238:241], v[60:63]
	s_setprio 0
	s_setprio 1
	v_mfma_f32_16x16x32_bf16 v[44:47], v[154:157], v[170:173], v[44:47]
	v_mfma_f32_16x16x32_bf16 v[12:15], v[162:165], v[170:173], v[12:15]
	v_mfma_f32_16x16x32_bf16 v[40:43], v[154:157], v[178:181], v[40:43]
	v_mfma_f32_16x16x32_bf16 v[8:11], v[162:165], v[178:181], v[8:11]
	v_mfma_f32_16x16x32_bf16 v[32:35], v[154:157], v[192:195], v[32:35]
	v_mfma_f32_16x16x32_bf16 v[4:7], v[162:165], v[192:195], v[4:7]
	v_mfma_f32_16x16x32_bf16 v[28:31], v[154:157], v[234:237], v[28:31]
	v_mfma_f32_16x16x32_bf16 v[0:3], v[162:165], v[234:237], v[0:3]
	v_mfma_f32_16x16x32_bf16 v[44:47], v[158:161], v[174:177], v[44:47]
	v_mfma_f32_16x16x32_bf16 v[12:15], v[166:169], v[174:177], v[12:15]
	v_mfma_f32_16x16x32_bf16 v[40:43], v[158:161], v[182:185], v[40:43]
	v_mfma_f32_16x16x32_bf16 v[8:11], v[166:169], v[182:185], v[8:11]
	v_mfma_f32_16x16x32_bf16 v[32:35], v[158:161], v[230:233], v[32:35]
	v_mfma_f32_16x16x32_bf16 v[4:7], v[166:169], v[230:233], v[4:7]
	v_mfma_f32_16x16x32_bf16 v[28:31], v[158:161], v[238:241], v[28:31]
	v_mfma_f32_16x16x32_bf16 v[0:3], v[166:169], v[238:241], v[0:3]
	s_setprio 0
	s_barrier
	s_add_i32 s68, 0, 0x18000
	s_add_i32 s69, 0, 0x1c000
	v_add_u32_e32 v150, s68, v140
	v_add_u32_e32 v166, s69, v140
	ds_read_b128 v[134:137], v150
	ds_read_b128 v[142:145], v150 offset:1024
	ds_read_b128 v[146:149], v150 offset:2048
	ds_read_b128 v[150:153], v150 offset:3072
	ds_read_b128 v[154:157], v166
	ds_read_b128 v[158:161], v166 offset:1024
	ds_read_b128 v[162:165], v166 offset:2048
	ds_read_b128 v[166:169], v166 offset:3072
	s_add_u32 s22, s28, 0xb0000
	s_addc_u32 s23, s29, 0
	s_mov_b32 m0, s44
	v_lshl_add_u64 v[246:247], s[22:23], 0, v[188:189]
	ds_read_b128 v[170:173], v141 offset:32768
	ds_read_b128 v[174:177], v141 offset:33792
	ds_read_b128 v[178:181], v141 offset:34816
	ds_read_b128 v[182:185], v141 offset:35840
	ds_read_b128 v[192:195], v141 offset:36864
	ds_read_b128 v[230:233], v141 offset:37888
	ds_read_b128 v[234:237], v141 offset:38912
	ds_read_b128 v[238:241], v141 offset:39936
	global_load_lds_dwordx4 v[246:247], off
	s_mov_b32 m0, s45
	v_lshl_add_u64 v[246:247], s[22:23], 0, v[128:129]
	global_load_lds_dwordx4 v[246:247], off
	s_waitcnt vmcnt(8)
	s_waitcnt lgkmcnt(0)
	s_barrier
	s_setprio 1
	s_waitcnt lgkmcnt(0)
	v_mfma_f32_16x16x32_bf16 v[124:127], v[134:137], v[170:173], v[124:127]
	v_mfma_f32_16x16x32_bf16 v[96:99], v[146:149], v[170:173], v[96:99]
	v_mfma_f32_16x16x32_bf16 v[120:123], v[134:137], v[178:181], v[120:123]
	v_mfma_f32_16x16x32_bf16 v[92:95], v[146:149], v[178:181], v[92:95]
	v_mfma_f32_16x16x32_bf16 v[116:119], v[134:137], v[192:195], v[116:119]
	v_mfma_f32_16x16x32_bf16 v[84:87], v[146:149], v[192:195], v[84:87]
	v_mfma_f32_16x16x32_bf16 v[112:115], v[134:137], v[234:237], v[112:115]
	v_mfma_f32_16x16x32_bf16 v[80:83], v[146:149], v[234:237], v[80:83]
	v_mfma_f32_16x16x32_bf16 v[124:127], v[142:145], v[174:177], v[124:127]
	v_mfma_f32_16x16x32_bf16 v[96:99], v[150:153], v[174:177], v[96:99]
	v_mfma_f32_16x16x32_bf16 v[120:123], v[142:145], v[182:185], v[120:123]
	v_mfma_f32_16x16x32_bf16 v[92:95], v[150:153], v[182:185], v[92:95]
	v_mfma_f32_16x16x32_bf16 v[116:119], v[142:145], v[230:233], v[116:119]
	v_mfma_f32_16x16x32_bf16 v[84:87], v[150:153], v[230:233], v[84:87]
	v_mfma_f32_16x16x32_bf16 v[112:115], v[142:145], v[238:241], v[112:115]
	v_mfma_f32_16x16x32_bf16 v[80:83], v[150:153], v[238:241], v[80:83]
	s_setprio 0
	s_setprio 1
	v_mfma_f32_16x16x32_bf16 v[64:67], v[154:157], v[170:173], v[64:67]
	v_mfma_f32_16x16x32_bf16 v[36:39], v[162:165], v[170:173], v[36:39]
	v_mfma_f32_16x16x32_bf16 v[56:59], v[154:157], v[178:181], v[56:59]
	v_mfma_f32_16x16x32_bf16 v[24:27], v[162:165], v[178:181], v[24:27]
	v_mfma_f32_16x16x32_bf16 v[52:55], v[154:157], v[192:195], v[52:55]
	v_mfma_f32_16x16x32_bf16 v[20:23], v[162:165], v[192:195], v[20:23]
	v_mfma_f32_16x16x32_bf16 v[48:51], v[154:157], v[234:237], v[48:51]
	v_mfma_f32_16x16x32_bf16 v[16:19], v[162:165], v[234:237], v[16:19]
	v_mfma_f32_16x16x32_bf16 v[64:67], v[158:161], v[174:177], v[64:67]
	v_mfma_f32_16x16x32_bf16 v[36:39], v[166:169], v[174:177], v[36:39]
	v_mfma_f32_16x16x32_bf16 v[56:59], v[158:161], v[182:185], v[56:59]
	v_mfma_f32_16x16x32_bf16 v[24:27], v[166:169], v[182:185], v[24:27]
	v_mfma_f32_16x16x32_bf16 v[52:55], v[158:161], v[230:233], v[52:55]
	v_mfma_f32_16x16x32_bf16 v[20:23], v[166:169], v[230:233], v[20:23]
	v_mfma_f32_16x16x32_bf16 v[48:51], v[158:161], v[238:241], v[48:51]
	v_mfma_f32_16x16x32_bf16 v[16:19], v[166:169], v[238:241], v[16:19]
	s_setprio 0
	s_barrier
; #define PG8_STAGE(bufoff, gbase, voff) do { _Pragma("unroll") for (int _i = 0; _i < 2; ++_i) \
;         __builtin_amdgcn_global_load_lds((const unsigned*)((const char*)(gbase) + (voff)[_i]), (PG8_LAS unsigned*)(lds + (bufoff) + ldsw + _i * 8192), 16, 0, 0); } while (0)
; #define PG8_LDA(dst, b, h) do { _Pragma("unroll") for (int m = 0; m < 4; ++m) _Pragma("unroll") for (int k = 0; k < 2; ++k) dst[m][k] = *(const PG8_LAS bf16x8*)(lds + PG8_SA(b, h) + aoff + m * 2048 + k * 1024); } while (0)
; #define PG8_MMA(ai, bj, At, Bt) do { __builtin_amdgcn_s_setprio(1); _Pragma("unroll") for (int m = 0; m < 4; ++m) _Pragma("unroll") for (int n = 0; n < 2; ++n) _Pragma("unroll") for (int k = 0; k < 2; ++k) \
;         acc[ai][bj][m][n] = __builtin_amdgcn_mfma_f32_16x16x32_bf16(Bt[n][k], At[m][k], acc[ai][bj][m][n], 0, 0, 0); __builtin_amdgcn_s_setprio(0); } while (0)
; #define PG8_WAIT_V(n) asm volatile("s_waitcnt vmcnt(" #n ")" ::: "memory")
; #define PG8_WAIT_L(n) asm volatile("s_waitcnt lgkmcnt(" #n ")" ::: "memory")
; #define PG8_BAR __builtin_amdgcn_s_barrier()
; #define PG8_SCHED __builtin_amdgcn_sched_barrier(0)
; template <class Epi, class Sched, bool ALIGN_EPI = false, bool SP2 = false>
; __device__ __forceinline__ void gemm_phase(PG8_LAS unsigned char* lds, const Gemm g, const Sched& S, const Epi& E) {
;     ...
;         for (int t = 0; t < nt; t += 2) {
;     ...
;             PG8_LDA(At, 1, 1); PG8_STAGE(PG8_SB(1, 0), b3, voffB); PG8_STAGE(PG8_SB(1, 1), b3 + hstepB, voffB); PG8_STAGE(PG8_SA(1, 0), a3, voffA);
;             PG8_WAIT_V(8); PG8_WAIT_L(0); PG8_BAR; PG8_MMA(1, 0, At, B0); PG8_MMA(1, 1, At, B1); PG8_BAR; PG8_SCHED;
	s_add_i32 s22, s68, s35
	v_lshl_add_u64 v[186:187], v[186:187], 0, s[94:95]
	s_mov_b32 m0, s22
	ds_read_b128 v[170:173], v141 offset:49152
	ds_read_b128 v[174:177], v141 offset:50176
	ds_read_b128 v[178:181], v141 offset:51200
	ds_read_b128 v[182:185], v141 offset:52224
	ds_read_b128 v[192:195], v141 offset:53248
	ds_read_b128 v[230:233], v141 offset:54272
	ds_read_b128 v[234:237], v141 offset:55296
	ds_read_b128 v[238:241], v141 offset:56320
	global_load_lds_dwordx4 v[186:187], off
	s_add_i32 m0, s22, 0x2000
	s_add_u32 s22, s26, 0xb0080
	v_lshl_add_u64 v[186:187], v[196:197], 0, s[94:95]
	s_addc_u32 s23, s27, 0
	s_add_i32 s26, s69, s35
	global_load_lds_dwordx4 v[186:187], off
	s_mov_b32 m0, s26
	v_lshl_add_u64 v[186:187], s[22:23], 0, v[188:189]
	global_load_lds_dwordx4 v[186:187], off
	s_add_i32 m0, s26, 0x2000
	v_lshl_add_u64 v[186:187], s[22:23], 0, v[128:129]
	global_load_lds_dwordx4 v[186:187], off
	s_mov_b32 m0, s57
	v_lshl_add_u64 v[186:187], v[242:243], 0, s[94:95]
	global_load_lds_dwordx4 v[186:187], off
	s_mov_b32 m0, s58
	v_lshl_add_u64 v[186:187], v[244:245], 0, s[94:95]
	global_load_lds_dwordx4 v[186:187], off
	s_waitcnt vmcnt(8)
	s_waitcnt lgkmcnt(0)
	s_barrier
	s_setprio 1
	s_waitcnt lgkmcnt(0)
	v_mfma_f32_16x16x32_bf16 v[108:111], v[134:137], v[170:173], v[108:111]
	v_mfma_f32_16x16x32_bf16 v[76:79], v[146:149], v[170:173], v[76:79]
	v_mfma_f32_16x16x32_bf16 v[104:107], v[134:137], v[178:181], v[104:107]
	v_mfma_f32_16x16x32_bf16 v[72:75], v[146:149], v[178:181], v[72:75]
	v_mfma_f32_16x16x32_bf16 v[100:103], v[134:137], v[192:195], v[100:103]
	v_mfma_f32_16x16x32_bf16 v[68:71], v[146:149], v[192:195], v[68:71]
	v_mfma_f32_16x16x32_bf16 v[88:91], v[134:137], v[234:237], v[88:91]
	v_mfma_f32_16x16x32_bf16 v[60:63], v[146:149], v[234:237], v[60:63]
	v_mfma_f32_16x16x32_bf16 v[108:111], v[142:145], v[174:177], v[108:111]
	v_mfma_f32_16x16x32_bf16 v[76:79], v[150:153], v[174:177], v[76:79]
	v_mfma_f32_16x16x32_bf16 v[104:107], v[142:145], v[182:185], v[104:107]
	v_mfma_f32_16x16x32_bf16 v[72:75], v[150:153], v[182:185], v[72:75]
	v_mfma_f32_16x16x32_bf16 v[100:103], v[142:145], v[230:233], v[100:103]
	v_mfma_f32_16x16x32_bf16 v[68:71], v[150:153], v[230:233], v[68:71]
	v_mfma_f32_16x16x32_bf16 v[88:91], v[142:145], v[238:241], v[88:91]
	v_mfma_f32_16x16x32_bf16 v[60:63], v[150:153], v[238:241], v[60:63]
	s_setprio 0
	s_setprio 1
	v_mfma_f32_16x16x32_bf16 v[44:47], v[154:157], v[170:173], v[44:47]
	v_mfma_f32_16x16x32_bf16 v[12:15], v[162:165], v[170:173], v[12:15]
	v_mfma_f32_16x16x32_bf16 v[40:43], v[154:157], v[178:181], v[40:43]
	v_mfma_f32_16x16x32_bf16 v[8:11], v[162:165], v[178:181], v[8:11]
	v_mfma_f32_16x16x32_bf16 v[32:35], v[154:157], v[192:195], v[32:35]
	v_mfma_f32_16x16x32_bf16 v[4:7], v[162:165], v[192:195], v[4:7]
	v_mfma_f32_16x16x32_bf16 v[28:31], v[154:157], v[234:237], v[28:31]
	v_mfma_f32_16x16x32_bf16 v[0:3], v[162:165], v[234:237], v[0:3]
	v_mfma_f32_16x16x32_bf16 v[44:47], v[158:161], v[174:177], v[44:47]
	v_mfma_f32_16x16x32_bf16 v[12:15], v[166:169], v[174:177], v[12:15]
	v_mfma_f32_16x16x32_bf16 v[40:43], v[158:161], v[182:185], v[40:43]
	v_mfma_f32_16x16x32_bf16 v[8:11], v[166:169], v[182:185], v[8:11]
	v_mfma_f32_16x16x32_bf16 v[32:35], v[158:161], v[230:233], v[32:35]
	v_mfma_f32_16x16x32_bf16 v[4:7], v[166:169], v[230:233], v[4:7]
	v_mfma_f32_16x16x32_bf16 v[28:31], v[158:161], v[238:241], v[28:31]
	v_mfma_f32_16x16x32_bf16 v[0:3], v[166:169], v[238:241], v[0:3]
	s_setprio 0
	s_barrier
	s_add_i32 s67, s67, 2
	s_add_u32 s65, s65, 0x100
	s_addc_u32 s66, s66, 0
	s_cmp_gt_u32 s67, 41
	s_mov_b64 s[22:23], s[24:25]
	s_cbranch_scc0 .LBB0_1993
	s_and_b64 vcc, exec, s[14:15]
	s_cbranch_vccz .LBB0_1996
	s_barrier
